# v45 minus the back-to-back s_setprio 0/1 pairs between the two MMA blocks of each GEMM super-phase
# speedup vs baseline: 1.0016x; 1.0016x over previous
; #define PG8_STAGE(bufoff, gbase, voff) do { _Pragma("unroll") for (int _i = 0; _i < 2; ++_i) \
;         __builtin_amdgcn_global_load_lds((const unsigned*)((const char*)(gbase) + (voff)[_i]), (PG8_LAS unsigned*)(lds + (bufoff) + ldsw + _i * 8192), 16, 0, 0); } while (0)
; #define PG8_LDA(dst, b, h) do { _Pragma("unroll") for (int m = 0; m < 4; ++m) _Pragma("unroll") for (int k = 0; k < 2; ++k) dst[m][k] = *(const PG8_LAS bf16x8*)(lds + PG8_SA(b, h) + aoff + m * 2048 + k * 1024); } while (0)
; #define PG8_LDB(dst, b, h) do { _Pragma("unroll") for (int n = 0; n < 2; ++n) _Pragma("unroll") for (int k = 0; k < 2; ++k) dst[n][k] = *(const PG8_LAS bf16x8*)(lds + PG8_SB(b, h) + boff + n * 2048 + k * 1024); } while (0)
; #define PG8_MMA(ai, bj, At, Bt) do { __builtin_amdgcn_s_setprio(1); _Pragma("unroll") for (int m = 0; m < 4; ++m) _Pragma("unroll") for (int n = 0; n < 2; ++n) _Pragma("unroll") for (int k = 0; k < 2; ++k) \
;         acc[ai][bj][m][n] = __builtin_amdgcn_mfma_f32_16x16x32_bf16(Bt[n][k], At[m][k], acc[ai][bj][m][n], 0, 0, 0); __builtin_amdgcn_s_setprio(0); } while (0)
; #define PG8_WAIT_V(n) asm volatile("s_waitcnt vmcnt(" #n ")" ::: "memory")
; #define PG8_WAIT_L(n) asm volatile("s_waitcnt lgkmcnt(" #n ")" ::: "memory")
; #define PG8_BAR __builtin_amdgcn_s_barrier()
; #define PG8_SCHED __builtin_amdgcn_sched_barrier(0)
; template <class Epi, class Sched, bool ALIGN_EPI = false, bool SP2 = false>
; __device__ __forceinline__ void gemm_phase(PG8_LAS unsigned char* lds, const Gemm g, const Sched& S, const Epi& E) {
;     ...
;             PG8_LDB(B0, 0, 0); PG8_LDB(B1, 0, 1); PG8_SCHED; PG8_LDA(At, 0, 0); PG8_STAGE(PG8_SA(1, 1), a1 + hstep, voffA);
;             PG8_WAIT_V(8); PG8_WAIT_L(0); PG8_BAR; PG8_MMA(0, 0, At, B0); PG8_MMA(0, 1, At, B1); PG8_BAR; PG8_SCHED;
;             PG8_LDA(At, 0, 1); PG8_STAGE(PG8_SB(0, 0), b2, voffB); PG8_STAGE(PG8_SB(0, 1), b2 + hstep, voffB); PG8_STAGE(PG8_SA(0, 0), a2, voffA);
;             PG8_WAIT_V(8); PG8_WAIT_L(0); PG8_BAR; PG8_MMA(1, 0, At, B0); PG8_MMA(1, 1, At, B1); PG8_BAR; PG8_SCHED;
.LBB0_99:
	ds_read_b128 v[154:157], v151
	ds_read_b128 v[158:161], v151 offset:1024
	ds_read_b128 v[166:169], v151 offset:2048
	ds_read_b128 v[170:173], v151 offset:3072
	ds_read_b128 v[174:177], v152
	ds_read_b128 v[178:181], v152 offset:1024
	ds_read_b128 v[182:185], v152 offset:2048
	ds_read_b128 v[186:189], v152 offset:3072
	s_add_u32 s24, s22, 0xfffc0080
	s_addc_u32 s25, s23, -1
	s_cmp_eq_u32 s47, 12
	s_cselect_b32 s27, s15, s25
	s_cselect_b32 s26, s43, s24
	s_cselect_b32 s25, s13, s46
	s_cselect_b32 s24, s44, s45
	v_lshl_add_u64 v[146:147], s[22:23], 0, v[138:139]
	s_add_i32 m0, s21, 0xc000
	ds_read_b128 v[190:193], v153
	ds_read_b128 v[194:197], v153 offset:1024
	ds_read_b128 v[198:201], v153 offset:2048
	ds_read_b128 v[202:205], v153 offset:3072
	ds_read_b128 v[206:209], v153 offset:4096
	ds_read_b128 v[210:213], v153 offset:5120
	ds_read_b128 v[214:217], v153 offset:6144
	ds_read_b128 v[218:221], v153 offset:7168
	global_load_lds_dwordx4 v[146:147], off
	v_lshl_add_u64 v[146:147], s[22:23], 0, v[140:141]
	s_add_i32 m0, s21, 0xe000
	s_nop 0
	global_load_lds_dwordx4 v[146:147], off
	s_waitcnt vmcnt(8)
	s_waitcnt lgkmcnt(0)
	s_barrier
	s_setprio 1
	s_waitcnt lgkmcnt(0)
	v_mfma_f32_16x16x32_bf16 v[118:121], v[154:157], v[190:193], v[118:121]
	v_mfma_f32_16x16x32_bf16 v[114:117], v[166:169], v[190:193], v[114:117]
	v_mfma_f32_16x16x32_bf16 v[110:113], v[154:157], v[198:201], v[110:113]
	v_mfma_f32_16x16x32_bf16 v[106:109], v[166:169], v[198:201], v[106:109]
	v_mfma_f32_16x16x32_bf16 v[94:97], v[154:157], v[206:209], v[94:97]
	v_mfma_f32_16x16x32_bf16 v[90:93], v[166:169], v[206:209], v[90:93]
	v_mfma_f32_16x16x32_bf16 v[78:81], v[154:157], v[214:217], v[78:81]
	v_mfma_f32_16x16x32_bf16 v[74:77], v[166:169], v[214:217], v[74:77]
	v_mfma_f32_16x16x32_bf16 v[118:121], v[158:161], v[194:197], v[118:121]
	v_mfma_f32_16x16x32_bf16 v[114:117], v[170:173], v[194:197], v[114:117]
	v_mfma_f32_16x16x32_bf16 v[110:113], v[158:161], v[202:205], v[110:113]
	v_mfma_f32_16x16x32_bf16 v[106:109], v[170:173], v[202:205], v[106:109]
	v_mfma_f32_16x16x32_bf16 v[94:97], v[158:161], v[210:213], v[94:97]
	v_mfma_f32_16x16x32_bf16 v[90:93], v[170:173], v[210:213], v[90:93]
	v_mfma_f32_16x16x32_bf16 v[78:81], v[158:161], v[218:221], v[78:81]
	v_mfma_f32_16x16x32_bf16 v[74:77], v[170:173], v[218:221], v[74:77]
	v_mfma_f32_16x16x32_bf16 v[126:129], v[174:177], v[190:193], v[126:129]
	v_mfma_f32_16x16x32_bf16 v[122:125], v[182:185], v[190:193], v[122:125]
	v_mfma_f32_16x16x32_bf16 v[102:105], v[174:177], v[198:201], v[102:105]
	v_mfma_f32_16x16x32_bf16 v[98:101], v[182:185], v[198:201], v[98:101]
	v_mfma_f32_16x16x32_bf16 v[86:89], v[174:177], v[206:209], v[86:89]
	v_mfma_f32_16x16x32_bf16 v[82:85], v[182:185], v[206:209], v[82:85]
	v_mfma_f32_16x16x32_bf16 v[70:73], v[174:177], v[214:217], v[70:73]
	v_mfma_f32_16x16x32_bf16 v[66:69], v[182:185], v[214:217], v[66:69]
	v_mfma_f32_16x16x32_bf16 v[126:129], v[178:181], v[194:197], v[126:129]
	v_mfma_f32_16x16x32_bf16 v[122:125], v[186:189], v[194:197], v[122:125]
	v_mfma_f32_16x16x32_bf16 v[102:105], v[178:181], v[202:205], v[102:105]
	v_mfma_f32_16x16x32_bf16 v[98:101], v[186:189], v[202:205], v[98:101]
	v_mfma_f32_16x16x32_bf16 v[86:89], v[178:181], v[210:213], v[86:89]
	v_mfma_f32_16x16x32_bf16 v[82:85], v[186:189], v[210:213], v[82:85]
	v_mfma_f32_16x16x32_bf16 v[70:73], v[178:181], v[218:221], v[70:73]
	v_mfma_f32_16x16x32_bf16 v[66:69], v[186:189], v[218:221], v[66:69]
	s_setprio 0
	s_barrier
	s_add_i32 s33, s39, s29
	v_lshl_add_u64 v[146:147], s[24:25], 0, v[132:133]
	s_mov_b32 m0, s33
	ds_read_b128 v[190:193], v153 offset:16384
	ds_read_b128 v[194:197], v153 offset:17408
	ds_read_b128 v[198:201], v153 offset:18432
	ds_read_b128 v[202:205], v153 offset:19456
	ds_read_b128 v[206:209], v153 offset:20480
	ds_read_b128 v[210:213], v153 offset:21504
	ds_read_b128 v[214:217], v153 offset:22528
	ds_read_b128 v[218:221], v153 offset:23552
	global_load_lds_dwordx4 v[146:147], off
	s_add_i32 m0, s33, 0x2000
	s_add_u32 s48, s24, 0x40000
	v_lshl_add_u64 v[222:223], s[24:25], 0, v[136:137]
	s_addc_u32 s49, s25, 0
	s_add_i32 s33, s40, s29
	global_load_lds_dwordx4 v[222:223], off
	v_lshl_add_u64 v[224:225], s[48:49], 0, v[132:133]
	s_mov_b32 m0, s33
	v_lshl_add_u64 v[226:227], s[26:27], 0, v[134:135]
	global_load_lds_dwordx4 v[224:225], off
	v_lshl_add_u64 v[224:225], s[48:49], 0, v[136:137]
	s_add_i32 m0, s33, 0x2000
	s_nop 0
	global_load_lds_dwordx4 v[224:225], off
	v_lshl_add_u64 v[224:225], s[26:27], 0, v[130:131]
	s_mov_b32 m0, s21
	s_nop 0
	global_load_lds_dwordx4 v[224:225], off
	s_mov_b32 m0, s30
	s_nop 0
	global_load_lds_dwordx4 v[226:227], off
	s_waitcnt vmcnt(8)
	s_waitcnt lgkmcnt(0)
	s_barrier
; #define PG8_STAGE(bufoff, gbase, voff) do { _Pragma("unroll") for (int _i = 0; _i < 2; ++_i) \
;         __builtin_amdgcn_global_load_lds((const unsigned*)((const char*)(gbase) + (voff)[_i]), (PG8_LAS unsigned*)(lds + (bufoff) + ldsw + _i * 8192), 16, 0, 0); } while (0)
; #define PG8_LDA(dst, b, h) do { _Pragma("unroll") for (int m = 0; m < 4; ++m) _Pragma("unroll") for (int k = 0; k < 2; ++k) dst[m][k] = *(const PG8_LAS bf16x8*)(lds + PG8_SA(b, h) + aoff + m * 2048 + k * 1024); } while (0)
; #define PG8_LDB(dst, b, h) do { _Pragma("unroll") for (int n = 0; n < 2; ++n) _Pragma("unroll") for (int k = 0; k < 2; ++k) dst[n][k] = *(const PG8_LAS bf16x8*)(lds + PG8_SB(b, h) + boff + n * 2048 + k * 1024); } while (0)
; #define PG8_MMA(ai, bj, At, Bt) do { __builtin_amdgcn_s_setprio(1); _Pragma("unroll") for (int m = 0; m < 4; ++m) _Pragma("unroll") for (int n = 0; n < 2; ++n) _Pragma("unroll") for (int k = 0; k < 2; ++k) \
;         acc[ai][bj][m][n] = __builtin_amdgcn_mfma_f32_16x16x32_bf16(Bt[n][k], At[m][k], acc[ai][bj][m][n], 0, 0, 0); __builtin_amdgcn_s_setprio(0); } while (0)
; #define PG8_WAIT_V(n) asm volatile("s_waitcnt vmcnt(" #n ")" ::: "memory")
; #define PG8_WAIT_L(n) asm volatile("s_waitcnt lgkmcnt(" #n ")" ::: "memory")
; #define PG8_BAR __builtin_amdgcn_s_barrier()
; #define PG8_SCHED __builtin_amdgcn_sched_barrier(0)
; template <class Epi, class Sched, bool ALIGN_EPI = false, bool SP2 = false>
; __device__ __forceinline__ void gemm_phase(PG8_LAS unsigned char* lds, const Gemm g, const Sched& S, const Epi& E) {
;     ...
;             PG8_WAIT_V(8); PG8_WAIT_L(0); PG8_BAR; PG8_MMA(1, 0, At, B0); PG8_MMA(1, 1, At, B1); PG8_BAR; PG8_SCHED;
;             PG8_LDB(B0, 1, 0); PG8_LDB(B1, 1, 1); PG8_SCHED; PG8_LDA(At, 1, 0); PG8_STAGE(PG8_SA(0, 1), a2 + hstep, voffA);
;             PG8_WAIT_V(8); PG8_WAIT_L(0); PG8_BAR; PG8_MMA(0, 0, At, B0); PG8_MMA(0, 1, At, B1); PG8_BAR; PG8_SCHED;
	s_setprio 1
	s_waitcnt lgkmcnt(0)
	v_mfma_f32_16x16x32_bf16 v[62:65], v[154:157], v[190:193], v[62:65]
	v_mfma_f32_16x16x32_bf16 v[58:61], v[166:169], v[190:193], v[58:61]
	v_mfma_f32_16x16x32_bf16 v[46:49], v[154:157], v[198:201], v[46:49]
	v_mfma_f32_16x16x32_bf16 v[42:45], v[166:169], v[198:201], v[42:45]
	v_mfma_f32_16x16x32_bf16 v[30:33], v[154:157], v[206:209], v[30:33]
	v_mfma_f32_16x16x32_bf16 v[26:29], v[166:169], v[206:209], v[26:29]
	v_mfma_f32_16x16x32_bf16 v[14:17], v[154:157], v[214:217], v[14:17]
	v_mfma_f32_16x16x32_bf16 v[10:13], v[166:169], v[214:217], v[10:13]
	v_mfma_f32_16x16x32_bf16 v[62:65], v[158:161], v[194:197], v[62:65]
	v_mfma_f32_16x16x32_bf16 v[58:61], v[170:173], v[194:197], v[58:61]
	v_mfma_f32_16x16x32_bf16 v[46:49], v[158:161], v[202:205], v[46:49]
	v_mfma_f32_16x16x32_bf16 v[42:45], v[170:173], v[202:205], v[42:45]
	v_mfma_f32_16x16x32_bf16 v[30:33], v[158:161], v[210:213], v[30:33]
	v_mfma_f32_16x16x32_bf16 v[26:29], v[170:173], v[210:213], v[26:29]
	v_mfma_f32_16x16x32_bf16 v[14:17], v[158:161], v[218:221], v[14:17]
	v_mfma_f32_16x16x32_bf16 v[10:13], v[170:173], v[218:221], v[10:13]
	v_mfma_f32_16x16x32_bf16 v[54:57], v[174:177], v[190:193], v[54:57]
	v_mfma_f32_16x16x32_bf16 v[50:53], v[182:185], v[190:193], v[50:53]
	v_mfma_f32_16x16x32_bf16 v[38:41], v[174:177], v[198:201], v[38:41]
	v_mfma_f32_16x16x32_bf16 v[34:37], v[182:185], v[198:201], v[34:37]
	v_mfma_f32_16x16x32_bf16 v[22:25], v[174:177], v[206:209], v[22:25]
	v_mfma_f32_16x16x32_bf16 v[18:21], v[182:185], v[206:209], v[18:21]
	v_mfma_f32_16x16x32_bf16 v[6:9], v[174:177], v[214:217], v[6:9]
	v_mfma_f32_16x16x32_bf16 v[2:5], v[182:185], v[214:217], v[2:5]
	v_mfma_f32_16x16x32_bf16 v[54:57], v[178:181], v[194:197], v[54:57]
	v_mfma_f32_16x16x32_bf16 v[50:53], v[186:189], v[194:197], v[50:53]
	v_mfma_f32_16x16x32_bf16 v[38:41], v[178:181], v[202:205], v[38:41]
	v_mfma_f32_16x16x32_bf16 v[34:37], v[186:189], v[202:205], v[34:37]
	v_mfma_f32_16x16x32_bf16 v[22:25], v[178:181], v[210:213], v[22:25]
	v_mfma_f32_16x16x32_bf16 v[18:21], v[186:189], v[210:213], v[18:21]
	v_mfma_f32_16x16x32_bf16 v[6:9], v[178:181], v[218:221], v[6:9]
	v_mfma_f32_16x16x32_bf16 v[2:5], v[186:189], v[218:221], v[2:5]
	s_setprio 0
	s_barrier
	s_add_i32 s33, 0, 0x18000
	v_add_u32_e32 v165, s33, v149
	s_add_i32 s48, 0, 0x1c000
	ds_read_b128 v[154:157], v165
	ds_read_b128 v[158:161], v165 offset:1024
	ds_read_b128 v[166:169], v165 offset:2048
	ds_read_b128 v[170:173], v165 offset:3072
	v_add_u32_e32 v165, s48, v149
	ds_read_b128 v[174:177], v165
	ds_read_b128 v[178:181], v165 offset:1024
	ds_read_b128 v[182:185], v165 offset:2048
	ds_read_b128 v[186:189], v165 offset:3072
	s_add_u32 s26, s26, 0x40000
	s_addc_u32 s27, s27, 0
	s_mov_b32 m0, s31
	v_lshl_add_u64 v[228:229], s[26:27], 0, v[130:131]
	ds_read_b128 v[190:193], v153 offset:32768
	ds_read_b128 v[194:197], v153 offset:33792
	ds_read_b128 v[198:201], v153 offset:34816
	ds_read_b128 v[202:205], v153 offset:35840
	ds_read_b128 v[206:209], v153 offset:36864
	ds_read_b128 v[210:213], v153 offset:37888
	ds_read_b128 v[214:217], v153 offset:38912
	ds_read_b128 v[218:221], v153 offset:39936
	global_load_lds_dwordx4 v[228:229], off
	v_lshl_add_u64 v[228:229], s[26:27], 0, v[134:135]
	s_mov_b32 m0, s34
	s_nop 0
	global_load_lds_dwordx4 v[228:229], off
	s_waitcnt vmcnt(8)
	s_waitcnt lgkmcnt(0)
	s_barrier
	s_setprio 1
	s_waitcnt lgkmcnt(0)
	v_mfma_f32_16x16x32_bf16 v[118:121], v[154:157], v[190:193], v[118:121]
	v_mfma_f32_16x16x32_bf16 v[114:117], v[166:169], v[190:193], v[114:117]
	v_mfma_f32_16x16x32_bf16 v[110:113], v[154:157], v[198:201], v[110:113]
	v_mfma_f32_16x16x32_bf16 v[106:109], v[166:169], v[198:201], v[106:109]
	v_mfma_f32_16x16x32_bf16 v[94:97], v[154:157], v[206:209], v[94:97]
	v_mfma_f32_16x16x32_bf16 v[90:93], v[166:169], v[206:209], v[90:93]
	v_mfma_f32_16x16x32_bf16 v[78:81], v[154:157], v[214:217], v[78:81]
	v_mfma_f32_16x16x32_bf16 v[74:77], v[166:169], v[214:217], v[74:77]
	v_mfma_f32_16x16x32_bf16 v[118:121], v[158:161], v[194:197], v[118:121]
	v_mfma_f32_16x16x32_bf16 v[114:117], v[170:173], v[194:197], v[114:117]
	v_mfma_f32_16x16x32_bf16 v[110:113], v[158:161], v[202:205], v[110:113]
	v_mfma_f32_16x16x32_bf16 v[106:109], v[170:173], v[202:205], v[106:109]
	v_mfma_f32_16x16x32_bf16 v[94:97], v[158:161], v[210:213], v[94:97]
	v_mfma_f32_16x16x32_bf16 v[90:93], v[170:173], v[210:213], v[90:93]
	v_mfma_f32_16x16x32_bf16 v[78:81], v[158:161], v[218:221], v[78:81]
	v_mfma_f32_16x16x32_bf16 v[74:77], v[170:173], v[218:221], v[74:77]
	v_mfma_f32_16x16x32_bf16 v[126:129], v[174:177], v[190:193], v[126:129]
	v_mfma_f32_16x16x32_bf16 v[122:125], v[182:185], v[190:193], v[122:125]
	v_mfma_f32_16x16x32_bf16 v[102:105], v[174:177], v[198:201], v[102:105]
	v_mfma_f32_16x16x32_bf16 v[98:101], v[182:185], v[198:201], v[98:101]
	v_mfma_f32_16x16x32_bf16 v[86:89], v[174:177], v[206:209], v[86:89]
	v_mfma_f32_16x16x32_bf16 v[82:85], v[182:185], v[206:209], v[82:85]
	v_mfma_f32_16x16x32_bf16 v[70:73], v[174:177], v[214:217], v[70:73]
	v_mfma_f32_16x16x32_bf16 v[66:69], v[182:185], v[214:217], v[66:69]
	v_mfma_f32_16x16x32_bf16 v[126:129], v[178:181], v[194:197], v[126:129]
	v_mfma_f32_16x16x32_bf16 v[122:125], v[186:189], v[194:197], v[122:125]
	v_mfma_f32_16x16x32_bf16 v[102:105], v[178:181], v[202:205], v[102:105]
	v_mfma_f32_16x16x32_bf16 v[98:101], v[186:189], v[202:205], v[98:101]
	v_mfma_f32_16x16x32_bf16 v[86:89], v[178:181], v[210:213], v[86:89]
	v_mfma_f32_16x16x32_bf16 v[82:85], v[186:189], v[210:213], v[82:85]
	v_mfma_f32_16x16x32_bf16 v[70:73], v[178:181], v[218:221], v[70:73]
	v_mfma_f32_16x16x32_bf16 v[66:69], v[186:189], v[218:221], v[66:69]
	s_setprio 0
	s_barrier
; #define PG8_STAGE(bufoff, gbase, voff) do { _Pragma("unroll") for (int _i = 0; _i < 2; ++_i) \
;         __builtin_amdgcn_global_load_lds((const unsigned*)((const char*)(gbase) + (voff)[_i]), (PG8_LAS unsigned*)(lds + (bufoff) + ldsw + _i * 8192), 16, 0, 0); } while (0)
; #define PG8_LDA(dst, b, h) do { _Pragma("unroll") for (int m = 0; m < 4; ++m) _Pragma("unroll") for (int k = 0; k < 2; ++k) dst[m][k] = *(const PG8_LAS bf16x8*)(lds + PG8_SA(b, h) + aoff + m * 2048 + k * 1024); } while (0)
; #define PG8_MMA(ai, bj, At, Bt) do { __builtin_amdgcn_s_setprio(1); _Pragma("unroll") for (int m = 0; m < 4; ++m) _Pragma("unroll") for (int n = 0; n < 2; ++n) _Pragma("unroll") for (int k = 0; k < 2; ++k) \
;         acc[ai][bj][m][n] = __builtin_amdgcn_mfma_f32_16x16x32_bf16(Bt[n][k], At[m][k], acc[ai][bj][m][n], 0, 0, 0); __builtin_amdgcn_s_setprio(0); } while (0)
; #define PG8_WAIT_V(n) asm volatile("s_waitcnt vmcnt(" #n ")" ::: "memory")
; #define PG8_WAIT_L(n) asm volatile("s_waitcnt lgkmcnt(" #n ")" ::: "memory")
; #define PG8_BAR __builtin_amdgcn_s_barrier()
; #define PG8_SCHED __builtin_amdgcn_sched_barrier(0)
; template <class Epi, class Sched, bool ALIGN_EPI = false, bool SP2 = false>
; __device__ __forceinline__ void gemm_phase(PG8_LAS unsigned char* lds, const Gemm g, const Sched& S, const Epi& E) {
;     ...
;         for (int t = 0; t < nt; t += 2) {
;             const bool last = (t == nt - 2);
;             const char* a1 = cA + (size_t)(t + 1) * kstep;
;             const char* a2 = last ? nA : cA + (size_t)(t + 2) * kstep; const char* b2 = last ? nB : cB + (size_t)(t + 2) * kstep;
;     ...
;             PG8_LDA(At, 1, 1); PG8_STAGE(PG8_SB(1, 0), b3, voffB); PG8_STAGE(PG8_SB(1, 1), b3 + hstep, voffB); PG8_STAGE(PG8_SA(1, 0), a3, voffA);
;             PG8_WAIT_V(8); PG8_WAIT_L(0); PG8_BAR; PG8_MMA(1, 0, At, B0); PG8_MMA(1, 1, At, B1); PG8_BAR; PG8_SCHED;
	s_add_i32 s26, s33, s29
	v_lshl_add_u64 v[146:147], v[146:147], 0, s[6:7]
	s_mov_b32 m0, s26
	ds_read_b128 v[190:193], v153 offset:49152
	ds_read_b128 v[194:197], v153 offset:50176
	ds_read_b128 v[198:201], v153 offset:51200
	ds_read_b128 v[202:205], v153 offset:52224
	ds_read_b128 v[206:209], v153 offset:53248
	ds_read_b128 v[210:213], v153 offset:54272
	ds_read_b128 v[214:217], v153 offset:55296
	ds_read_b128 v[218:221], v153 offset:56320
	global_load_lds_dwordx4 v[146:147], off
	s_add_i32 m0, s26, 0x2000
	s_add_u32 s24, s24, 0x40080
	v_lshl_add_u64 v[146:147], v[222:223], 0, s[6:7]
	s_addc_u32 s25, s25, 0
	s_add_i32 s26, s48, s29
	global_load_lds_dwordx4 v[146:147], off
	v_lshl_add_u64 v[146:147], s[24:25], 0, v[132:133]
	s_mov_b32 m0, s26
	s_nop 0
	global_load_lds_dwordx4 v[146:147], off
	v_lshl_add_u64 v[146:147], s[24:25], 0, v[136:137]
	s_add_i32 m0, s26, 0x2000
	s_nop 0
	global_load_lds_dwordx4 v[146:147], off
	v_lshl_add_u64 v[146:147], v[224:225], 0, s[6:7]
	s_mov_b32 m0, s36
	s_nop 0
	global_load_lds_dwordx4 v[146:147], off
	v_lshl_add_u64 v[146:147], v[226:227], 0, s[6:7]
	s_mov_b32 m0, s37
	s_nop 0
	global_load_lds_dwordx4 v[146:147], off
	s_waitcnt vmcnt(8)
	s_waitcnt lgkmcnt(0)
	s_barrier
	s_setprio 1
	s_waitcnt lgkmcnt(0)
	v_mfma_f32_16x16x32_bf16 v[62:65], v[154:157], v[190:193], v[62:65]
	v_mfma_f32_16x16x32_bf16 v[58:61], v[166:169], v[190:193], v[58:61]
	v_mfma_f32_16x16x32_bf16 v[46:49], v[154:157], v[198:201], v[46:49]
	v_mfma_f32_16x16x32_bf16 v[42:45], v[166:169], v[198:201], v[42:45]
	v_mfma_f32_16x16x32_bf16 v[30:33], v[154:157], v[206:209], v[30:33]
	v_mfma_f32_16x16x32_bf16 v[26:29], v[166:169], v[206:209], v[26:29]
	v_mfma_f32_16x16x32_bf16 v[14:17], v[154:157], v[214:217], v[14:17]
	v_mfma_f32_16x16x32_bf16 v[10:13], v[166:169], v[214:217], v[10:13]
	v_mfma_f32_16x16x32_bf16 v[62:65], v[158:161], v[194:197], v[62:65]
	v_mfma_f32_16x16x32_bf16 v[58:61], v[170:173], v[194:197], v[58:61]
	v_mfma_f32_16x16x32_bf16 v[46:49], v[158:161], v[202:205], v[46:49]
	v_mfma_f32_16x16x32_bf16 v[42:45], v[170:173], v[202:205], v[42:45]
	v_mfma_f32_16x16x32_bf16 v[30:33], v[158:161], v[210:213], v[30:33]
	v_mfma_f32_16x16x32_bf16 v[26:29], v[170:173], v[210:213], v[26:29]
	v_mfma_f32_16x16x32_bf16 v[14:17], v[158:161], v[218:221], v[14:17]
	v_mfma_f32_16x16x32_bf16 v[10:13], v[170:173], v[218:221], v[10:13]
	v_mfma_f32_16x16x32_bf16 v[54:57], v[174:177], v[190:193], v[54:57]
	v_mfma_f32_16x16x32_bf16 v[50:53], v[182:185], v[190:193], v[50:53]
	v_mfma_f32_16x16x32_bf16 v[38:41], v[174:177], v[198:201], v[38:41]
	v_mfma_f32_16x16x32_bf16 v[34:37], v[182:185], v[198:201], v[34:37]
	v_mfma_f32_16x16x32_bf16 v[22:25], v[174:177], v[206:209], v[22:25]
	v_mfma_f32_16x16x32_bf16 v[18:21], v[182:185], v[206:209], v[18:21]
	v_mfma_f32_16x16x32_bf16 v[6:9], v[174:177], v[214:217], v[6:9]
	v_mfma_f32_16x16x32_bf16 v[2:5], v[182:185], v[214:217], v[2:5]
	v_mfma_f32_16x16x32_bf16 v[54:57], v[178:181], v[194:197], v[54:57]
	v_mfma_f32_16x16x32_bf16 v[50:53], v[186:189], v[194:197], v[50:53]
	v_mfma_f32_16x16x32_bf16 v[38:41], v[178:181], v[202:205], v[38:41]
	v_mfma_f32_16x16x32_bf16 v[34:37], v[186:189], v[202:205], v[34:37]
	v_mfma_f32_16x16x32_bf16 v[22:25], v[178:181], v[210:213], v[22:25]
	v_mfma_f32_16x16x32_bf16 v[18:21], v[186:189], v[210:213], v[18:21]
	v_mfma_f32_16x16x32_bf16 v[6:9], v[178:181], v[218:221], v[6:9]
	v_mfma_f32_16x16x32_bf16 v[2:5], v[186:189], v[218:221], v[2:5]
	s_setprio 0
	s_barrier
	s_add_i32 s47, s47, 2
	s_add_u32 s22, s22, 0x100
	s_addc_u32 s23, s23, 0
	s_add_u32 s45, s45, 0x100
	s_addc_u32 s46, s46, 0
	s_cmp_gt_u32 s47, 13
	s_cbranch_scc0 .LBB0_99
	s_and_b64 vcc, exec, s[10:11]
	s_cbranch_vccz .LBB0_102
	s_barrier

; #define PG8_STAGE(bufoff, gbase, voff) do { _Pragma("unroll") for (int _i = 0; _i < 2; ++_i) \
;         __builtin_amdgcn_global_load_lds((const unsigned*)((const char*)(gbase) + (voff)[_i]), (PG8_LAS unsigned*)(lds + (bufoff) + ldsw + _i * 8192), 16, 0, 0); } while (0)
; #define PG8_LDA(dst, b, h) do { _Pragma("unroll") for (int m = 0; m < 4; ++m) _Pragma("unroll") for (int k = 0; k < 2; ++k) dst[m][k] = *(const PG8_LAS bf16x8*)(lds + PG8_SA(b, h) + aoff + m * 2048 + k * 1024); } while (0)
; #define PG8_LDB(dst, b, h) do { _Pragma("unroll") for (int n = 0; n < 2; ++n) _Pragma("unroll") for (int k = 0; k < 2; ++k) dst[n][k] = *(const PG8_LAS bf16x8*)(lds + PG8_SB(b, h) + boff + n * 2048 + k * 1024); } while (0)
; #define PG8_MMA(ai, bj, At, Bt) do { __builtin_amdgcn_s_setprio(1); _Pragma("unroll") for (int m = 0; m < 4; ++m) _Pragma("unroll") for (int n = 0; n < 2; ++n) _Pragma("unroll") for (int k = 0; k < 2; ++k) \
;         acc[ai][bj][m][n] = __builtin_amdgcn_mfma_f32_16x16x32_bf16(Bt[n][k], At[m][k], acc[ai][bj][m][n], 0, 0, 0); __builtin_amdgcn_s_setprio(0); } while (0)
; #define PG8_WAIT_V(n) asm volatile("s_waitcnt vmcnt(" #n ")" ::: "memory")
; #define PG8_WAIT_L(n) asm volatile("s_waitcnt lgkmcnt(" #n ")" ::: "memory")
; #define PG8_BAR __builtin_amdgcn_s_barrier()
; #define PG8_SCHED __builtin_amdgcn_sched_barrier(0)
; template <class Epi, class Sched, bool ALIGN_EPI = false, bool SP2 = false>
; __device__ __forceinline__ void gemm_phase(PG8_LAS unsigned char* lds, const Gemm g, const Sched& S, const Epi& E) {
;     ...
;             PG8_LDB(B0, 0, 0); PG8_LDB(B1, 0, 1); PG8_SCHED; PG8_LDA(At, 0, 0); PG8_STAGE(PG8_SA(1, 1), a1 + hstep, voffA);
;             PG8_WAIT_V(8); PG8_WAIT_L(0); PG8_BAR; PG8_MMA(0, 0, At, B0); PG8_MMA(0, 1, At, B1); PG8_BAR; PG8_SCHED;
;             PG8_LDA(At, 0, 1); PG8_STAGE(PG8_SB(0, 0), b2, voffB); PG8_STAGE(PG8_SB(0, 1), b2 + hstep, voffB); PG8_STAGE(PG8_SA(0, 0), a2, voffA);
;             PG8_WAIT_V(8); PG8_WAIT_L(0); PG8_BAR; PG8_MMA(1, 0, At, B0); PG8_MMA(1, 1, At, B1); PG8_BAR; PG8_SCHED;
.LBB0_422:
	ds_read_b128 v[154:157], v151
	ds_read_b128 v[158:161], v151 offset:1024
	ds_read_b128 v[166:169], v151 offset:2048
	ds_read_b128 v[170:173], v151 offset:3072
	ds_read_b128 v[174:177], v152
	ds_read_b128 v[178:181], v152 offset:1024
	ds_read_b128 v[182:185], v152 offset:2048
	ds_read_b128 v[186:189], v152 offset:3072
	s_add_u32 s24, s22, 0x100
	s_addc_u32 s25, s23, 0
	s_cmp_eq_u32 s50, 40
	s_cselect_b32 s29, s1, s25
	s_cselect_b32 s28, s0, s24
	s_cselect_b32 s27, s21, s49
	s_cselect_b32 s26, s20, s48
	v_lshl_add_u64 v[146:147], s[22:23], 0, v[138:139]
	s_add_i32 m0, s34, 0xc000
	ds_read_b128 v[190:193], v153
	ds_read_b128 v[194:197], v153 offset:1024
	ds_read_b128 v[198:201], v153 offset:2048
	ds_read_b128 v[202:205], v153 offset:3072
	ds_read_b128 v[206:209], v153 offset:4096
	ds_read_b128 v[210:213], v153 offset:5120
	ds_read_b128 v[214:217], v153 offset:6144
	ds_read_b128 v[218:221], v153 offset:7168
	global_load_lds_dwordx4 v[146:147], off
	v_lshl_add_u64 v[146:147], s[22:23], 0, v[140:141]
	s_add_i32 m0, s34, 0xe000
	s_nop 0
	global_load_lds_dwordx4 v[146:147], off
	s_waitcnt vmcnt(8)
	s_waitcnt lgkmcnt(0)
	s_barrier
	s_setprio 1
	s_waitcnt lgkmcnt(0)
	v_mfma_f32_16x16x32_bf16 v[126:129], v[154:157], v[190:193], v[126:129]
	v_mfma_f32_16x16x32_bf16 v[122:125], v[166:169], v[190:193], v[122:125]
	v_mfma_f32_16x16x32_bf16 v[118:121], v[154:157], v[198:201], v[118:121]
	v_mfma_f32_16x16x32_bf16 v[110:113], v[166:169], v[198:201], v[110:113]
	v_mfma_f32_16x16x32_bf16 v[102:105], v[154:157], v[206:209], v[102:105]
	v_mfma_f32_16x16x32_bf16 v[94:97], v[166:169], v[206:209], v[94:97]
	v_mfma_f32_16x16x32_bf16 v[82:85], v[154:157], v[214:217], v[82:85]
	v_mfma_f32_16x16x32_bf16 v[74:77], v[166:169], v[214:217], v[74:77]
	v_mfma_f32_16x16x32_bf16 v[126:129], v[158:161], v[194:197], v[126:129]
	v_mfma_f32_16x16x32_bf16 v[122:125], v[170:173], v[194:197], v[122:125]
	v_mfma_f32_16x16x32_bf16 v[118:121], v[158:161], v[202:205], v[118:121]
	v_mfma_f32_16x16x32_bf16 v[110:113], v[170:173], v[202:205], v[110:113]
	v_mfma_f32_16x16x32_bf16 v[102:105], v[158:161], v[210:213], v[102:105]
	v_mfma_f32_16x16x32_bf16 v[94:97], v[170:173], v[210:213], v[94:97]
	v_mfma_f32_16x16x32_bf16 v[82:85], v[158:161], v[218:221], v[82:85]
	v_mfma_f32_16x16x32_bf16 v[74:77], v[170:173], v[218:221], v[74:77]
	v_mfma_f32_16x16x32_bf16 v[114:117], v[174:177], v[190:193], v[114:117]
	v_mfma_f32_16x16x32_bf16 v[106:109], v[182:185], v[190:193], v[106:109]
	v_mfma_f32_16x16x32_bf16 v[98:101], v[174:177], v[198:201], v[98:101]
	v_mfma_f32_16x16x32_bf16 v[90:93], v[182:185], v[198:201], v[90:93]
	v_mfma_f32_16x16x32_bf16 v[86:89], v[174:177], v[206:209], v[86:89]
	v_mfma_f32_16x16x32_bf16 v[78:81], v[182:185], v[206:209], v[78:81]
	v_mfma_f32_16x16x32_bf16 v[70:73], v[174:177], v[214:217], v[70:73]
	v_mfma_f32_16x16x32_bf16 v[66:69], v[182:185], v[214:217], v[66:69]
	v_mfma_f32_16x16x32_bf16 v[114:117], v[178:181], v[194:197], v[114:117]
	v_mfma_f32_16x16x32_bf16 v[106:109], v[186:189], v[194:197], v[106:109]
	v_mfma_f32_16x16x32_bf16 v[98:101], v[178:181], v[202:205], v[98:101]
	v_mfma_f32_16x16x32_bf16 v[90:93], v[186:189], v[202:205], v[90:93]
	v_mfma_f32_16x16x32_bf16 v[86:89], v[178:181], v[210:213], v[86:89]
	v_mfma_f32_16x16x32_bf16 v[78:81], v[186:189], v[210:213], v[78:81]
	v_mfma_f32_16x16x32_bf16 v[70:73], v[178:181], v[218:221], v[70:73]
	v_mfma_f32_16x16x32_bf16 v[66:69], v[186:189], v[218:221], v[66:69]
	s_setprio 0
	s_barrier
	s_add_i32 s22, s41, s31
	v_lshl_add_u64 v[146:147], s[26:27], 0, v[132:133]
	s_mov_b32 m0, s22
	ds_read_b128 v[190:193], v153 offset:16384
	ds_read_b128 v[194:197], v153 offset:17408
	ds_read_b128 v[198:201], v153 offset:18432
	ds_read_b128 v[202:205], v153 offset:19456
	ds_read_b128 v[206:209], v153 offset:20480
	ds_read_b128 v[210:213], v153 offset:21504
	ds_read_b128 v[214:217], v153 offset:22528
	ds_read_b128 v[218:221], v153 offset:23552
	global_load_lds_dwordx4 v[146:147], off
	s_add_i32 m0, s22, 0x2000
	s_add_u32 s22, s26, 0xb0000
	v_lshl_add_u64 v[222:223], s[26:27], 0, v[136:137]
	s_addc_u32 s23, s27, 0
	s_add_i32 s33, s43, s31
	global_load_lds_dwordx4 v[222:223], off
	v_lshl_add_u64 v[224:225], s[22:23], 0, v[132:133]
	s_mov_b32 m0, s33
	v_lshl_add_u64 v[226:227], s[28:29], 0, v[134:135]
	global_load_lds_dwordx4 v[224:225], off
	v_lshl_add_u64 v[224:225], s[22:23], 0, v[136:137]
	s_add_i32 m0, s33, 0x2000
	s_nop 0
	global_load_lds_dwordx4 v[224:225], off
	v_lshl_add_u64 v[224:225], s[28:29], 0, v[130:131]
	s_mov_b32 m0, s34
	s_nop 0
	global_load_lds_dwordx4 v[224:225], off
	s_mov_b32 m0, s35
	s_nop 0
	global_load_lds_dwordx4 v[226:227], off
	s_waitcnt vmcnt(8)
	s_waitcnt lgkmcnt(0)
	s_barrier
; #define PG8_STAGE(bufoff, gbase, voff) do { _Pragma("unroll") for (int _i = 0; _i < 2; ++_i) \
;         __builtin_amdgcn_global_load_lds((const unsigned*)((const char*)(gbase) + (voff)[_i]), (PG8_LAS unsigned*)(lds + (bufoff) + ldsw + _i * 8192), 16, 0, 0); } while (0)
; #define PG8_LDA(dst, b, h) do { _Pragma("unroll") for (int m = 0; m < 4; ++m) _Pragma("unroll") for (int k = 0; k < 2; ++k) dst[m][k] = *(const PG8_LAS bf16x8*)(lds + PG8_SA(b, h) + aoff + m * 2048 + k * 1024); } while (0)
; #define PG8_LDB(dst, b, h) do { _Pragma("unroll") for (int n = 0; n < 2; ++n) _Pragma("unroll") for (int k = 0; k < 2; ++k) dst[n][k] = *(const PG8_LAS bf16x8*)(lds + PG8_SB(b, h) + boff + n * 2048 + k * 1024); } while (0)
; #define PG8_MMA(ai, bj, At, Bt) do { __builtin_amdgcn_s_setprio(1); _Pragma("unroll") for (int m = 0; m < 4; ++m) _Pragma("unroll") for (int n = 0; n < 2; ++n) _Pragma("unroll") for (int k = 0; k < 2; ++k) \
;         acc[ai][bj][m][n] = __builtin_amdgcn_mfma_f32_16x16x32_bf16(Bt[n][k], At[m][k], acc[ai][bj][m][n], 0, 0, 0); __builtin_amdgcn_s_setprio(0); } while (0)
; #define PG8_WAIT_V(n) asm volatile("s_waitcnt vmcnt(" #n ")" ::: "memory")
; #define PG8_WAIT_L(n) asm volatile("s_waitcnt lgkmcnt(" #n ")" ::: "memory")
; #define PG8_BAR __builtin_amdgcn_s_barrier()
; #define PG8_SCHED __builtin_amdgcn_sched_barrier(0)
; template <class Epi, class Sched, bool ALIGN_EPI = false, bool SP2 = false>
; __device__ __forceinline__ void gemm_phase(PG8_LAS unsigned char* lds, const Gemm g, const Sched& S, const Epi& E) {
;     ...
;             PG8_WAIT_V(8); PG8_WAIT_L(0); PG8_BAR; PG8_MMA(1, 0, At, B0); PG8_MMA(1, 1, At, B1); PG8_BAR; PG8_SCHED;
;             PG8_LDB(B0, 1, 0); PG8_LDB(B1, 1, 1); PG8_SCHED; PG8_LDA(At, 1, 0); PG8_STAGE(PG8_SA(0, 1), a2 + hstep, voffA);
;             PG8_WAIT_V(8); PG8_WAIT_L(0); PG8_BAR; PG8_MMA(0, 0, At, B0); PG8_MMA(0, 1, At, B1); PG8_BAR; PG8_SCHED;
	s_setprio 1
	s_waitcnt lgkmcnt(0)
	v_mfma_f32_16x16x32_bf16 v[62:65], v[154:157], v[190:193], v[62:65]
	v_mfma_f32_16x16x32_bf16 v[58:61], v[166:169], v[190:193], v[58:61]
	v_mfma_f32_16x16x32_bf16 v[54:57], v[154:157], v[198:201], v[54:57]
	v_mfma_f32_16x16x32_bf16 v[46:49], v[166:169], v[198:201], v[46:49]
	v_mfma_f32_16x16x32_bf16 v[38:41], v[154:157], v[206:209], v[38:41]
	v_mfma_f32_16x16x32_bf16 v[30:33], v[166:169], v[206:209], v[30:33]
	v_mfma_f32_16x16x32_bf16 v[22:25], v[154:157], v[214:217], v[22:25]
	v_mfma_f32_16x16x32_bf16 v[14:17], v[166:169], v[214:217], v[14:17]
	v_mfma_f32_16x16x32_bf16 v[62:65], v[158:161], v[194:197], v[62:65]
	v_mfma_f32_16x16x32_bf16 v[58:61], v[170:173], v[194:197], v[58:61]
	v_mfma_f32_16x16x32_bf16 v[54:57], v[158:161], v[202:205], v[54:57]
	v_mfma_f32_16x16x32_bf16 v[46:49], v[170:173], v[202:205], v[46:49]
	v_mfma_f32_16x16x32_bf16 v[38:41], v[158:161], v[210:213], v[38:41]
	v_mfma_f32_16x16x32_bf16 v[30:33], v[170:173], v[210:213], v[30:33]
	v_mfma_f32_16x16x32_bf16 v[22:25], v[158:161], v[218:221], v[22:25]
	v_mfma_f32_16x16x32_bf16 v[14:17], v[170:173], v[218:221], v[14:17]
	v_mfma_f32_16x16x32_bf16 v[50:53], v[174:177], v[190:193], v[50:53]
	v_mfma_f32_16x16x32_bf16 v[42:45], v[182:185], v[190:193], v[42:45]
	v_mfma_f32_16x16x32_bf16 v[34:37], v[174:177], v[198:201], v[34:37]
	v_mfma_f32_16x16x32_bf16 v[26:29], v[182:185], v[198:201], v[26:29]
	v_mfma_f32_16x16x32_bf16 v[18:21], v[174:177], v[206:209], v[18:21]
	v_mfma_f32_16x16x32_bf16 v[10:13], v[182:185], v[206:209], v[10:13]
	v_mfma_f32_16x16x32_bf16 v[6:9], v[174:177], v[214:217], v[6:9]
	v_mfma_f32_16x16x32_bf16 v[2:5], v[182:185], v[214:217], v[2:5]
	v_mfma_f32_16x16x32_bf16 v[50:53], v[178:181], v[194:197], v[50:53]
	v_mfma_f32_16x16x32_bf16 v[42:45], v[186:189], v[194:197], v[42:45]
	v_mfma_f32_16x16x32_bf16 v[34:37], v[178:181], v[202:205], v[34:37]
	v_mfma_f32_16x16x32_bf16 v[26:29], v[186:189], v[202:205], v[26:29]
	v_mfma_f32_16x16x32_bf16 v[18:21], v[178:181], v[210:213], v[18:21]
	v_mfma_f32_16x16x32_bf16 v[10:13], v[186:189], v[210:213], v[10:13]
	v_mfma_f32_16x16x32_bf16 v[6:9], v[178:181], v[218:221], v[6:9]
	v_mfma_f32_16x16x32_bf16 v[2:5], v[186:189], v[218:221], v[2:5]
	s_setprio 0
	s_barrier
	s_add_i32 s33, 0, 0x18000
	v_add_u32_e32 v165, s33, v149
	s_add_i32 s51, 0, 0x1c000
	ds_read_b128 v[154:157], v165
	ds_read_b128 v[158:161], v165 offset:1024
	ds_read_b128 v[166:169], v165 offset:2048
	ds_read_b128 v[170:173], v165 offset:3072
	v_add_u32_e32 v165, s51, v149
	ds_read_b128 v[174:177], v165
	ds_read_b128 v[178:181], v165 offset:1024
	ds_read_b128 v[182:185], v165 offset:2048
	ds_read_b128 v[186:189], v165 offset:3072
	s_add_u32 s22, s28, 0xb0000
	s_addc_u32 s23, s29, 0
	s_mov_b32 m0, s36
	v_lshl_add_u64 v[228:229], s[22:23], 0, v[130:131]
	ds_read_b128 v[190:193], v153 offset:32768
	ds_read_b128 v[194:197], v153 offset:33792
	ds_read_b128 v[198:201], v153 offset:34816
	ds_read_b128 v[202:205], v153 offset:35840
	ds_read_b128 v[206:209], v153 offset:36864
	ds_read_b128 v[210:213], v153 offset:37888
	ds_read_b128 v[214:217], v153 offset:38912
	ds_read_b128 v[218:221], v153 offset:39936
	global_load_lds_dwordx4 v[228:229], off
	v_lshl_add_u64 v[228:229], s[22:23], 0, v[134:135]
	s_mov_b32 m0, s37
	s_nop 0
	global_load_lds_dwordx4 v[228:229], off
	s_waitcnt vmcnt(8)
	s_waitcnt lgkmcnt(0)
	s_barrier
	s_setprio 1
	s_waitcnt lgkmcnt(0)
	v_mfma_f32_16x16x32_bf16 v[126:129], v[154:157], v[190:193], v[126:129]
	v_mfma_f32_16x16x32_bf16 v[122:125], v[166:169], v[190:193], v[122:125]
	v_mfma_f32_16x16x32_bf16 v[118:121], v[154:157], v[198:201], v[118:121]
	v_mfma_f32_16x16x32_bf16 v[110:113], v[166:169], v[198:201], v[110:113]
	v_mfma_f32_16x16x32_bf16 v[102:105], v[154:157], v[206:209], v[102:105]
	v_mfma_f32_16x16x32_bf16 v[94:97], v[166:169], v[206:209], v[94:97]
	v_mfma_f32_16x16x32_bf16 v[82:85], v[154:157], v[214:217], v[82:85]
	v_mfma_f32_16x16x32_bf16 v[74:77], v[166:169], v[214:217], v[74:77]
	v_mfma_f32_16x16x32_bf16 v[126:129], v[158:161], v[194:197], v[126:129]
	v_mfma_f32_16x16x32_bf16 v[122:125], v[170:173], v[194:197], v[122:125]
	v_mfma_f32_16x16x32_bf16 v[118:121], v[158:161], v[202:205], v[118:121]
	v_mfma_f32_16x16x32_bf16 v[110:113], v[170:173], v[202:205], v[110:113]
	v_mfma_f32_16x16x32_bf16 v[102:105], v[158:161], v[210:213], v[102:105]
	v_mfma_f32_16x16x32_bf16 v[94:97], v[170:173], v[210:213], v[94:97]
	v_mfma_f32_16x16x32_bf16 v[82:85], v[158:161], v[218:221], v[82:85]
	v_mfma_f32_16x16x32_bf16 v[74:77], v[170:173], v[218:221], v[74:77]
	v_mfma_f32_16x16x32_bf16 v[114:117], v[174:177], v[190:193], v[114:117]
	v_mfma_f32_16x16x32_bf16 v[106:109], v[182:185], v[190:193], v[106:109]
	v_mfma_f32_16x16x32_bf16 v[98:101], v[174:177], v[198:201], v[98:101]
	v_mfma_f32_16x16x32_bf16 v[90:93], v[182:185], v[198:201], v[90:93]
	v_mfma_f32_16x16x32_bf16 v[86:89], v[174:177], v[206:209], v[86:89]
	v_mfma_f32_16x16x32_bf16 v[78:81], v[182:185], v[206:209], v[78:81]
	v_mfma_f32_16x16x32_bf16 v[70:73], v[174:177], v[214:217], v[70:73]
	v_mfma_f32_16x16x32_bf16 v[66:69], v[182:185], v[214:217], v[66:69]
	v_mfma_f32_16x16x32_bf16 v[114:117], v[178:181], v[194:197], v[114:117]
	v_mfma_f32_16x16x32_bf16 v[106:109], v[186:189], v[194:197], v[106:109]
	v_mfma_f32_16x16x32_bf16 v[98:101], v[178:181], v[202:205], v[98:101]
	v_mfma_f32_16x16x32_bf16 v[90:93], v[186:189], v[202:205], v[90:93]
	v_mfma_f32_16x16x32_bf16 v[86:89], v[178:181], v[210:213], v[86:89]
	v_mfma_f32_16x16x32_bf16 v[78:81], v[186:189], v[210:213], v[78:81]
	v_mfma_f32_16x16x32_bf16 v[70:73], v[178:181], v[218:221], v[70:73]
	v_mfma_f32_16x16x32_bf16 v[66:69], v[186:189], v[218:221], v[66:69]
	s_setprio 0
	s_barrier
; #define PG8_STAGE(bufoff, gbase, voff) do { _Pragma("unroll") for (int _i = 0; _i < 2; ++_i) \
;         __builtin_amdgcn_global_load_lds((const unsigned*)((const char*)(gbase) + (voff)[_i]), (PG8_LAS unsigned*)(lds + (bufoff) + ldsw + _i * 8192), 16, 0, 0); } while (0)
; #define PG8_LDA(dst, b, h) do { _Pragma("unroll") for (int m = 0; m < 4; ++m) _Pragma("unroll") for (int k = 0; k < 2; ++k) dst[m][k] = *(const PG8_LAS bf16x8*)(lds + PG8_SA(b, h) + aoff + m * 2048 + k * 1024); } while (0)
; #define PG8_MMA(ai, bj, At, Bt) do { __builtin_amdgcn_s_setprio(1); _Pragma("unroll") for (int m = 0; m < 4; ++m) _Pragma("unroll") for (int n = 0; n < 2; ++n) _Pragma("unroll") for (int k = 0; k < 2; ++k) \
;         acc[ai][bj][m][n] = __builtin_amdgcn_mfma_f32_16x16x32_bf16(Bt[n][k], At[m][k], acc[ai][bj][m][n], 0, 0, 0); __builtin_amdgcn_s_setprio(0); } while (0)
; #define PG8_WAIT_V(n) asm volatile("s_waitcnt vmcnt(" #n ")" ::: "memory")
; #define PG8_WAIT_L(n) asm volatile("s_waitcnt lgkmcnt(" #n ")" ::: "memory")
; #define PG8_BAR __builtin_amdgcn_s_barrier()
; #define PG8_SCHED __builtin_amdgcn_sched_barrier(0)
; template <class Epi, class Sched, bool ALIGN_EPI = false, bool SP2 = false>
; __device__ __forceinline__ void gemm_phase(PG8_LAS unsigned char* lds, const Gemm g, const Sched& S, const Epi& E) {
;     ...
;         for (int t = 0; t < nt; t += 2) {
;             const bool last = (t == nt - 2);
;             const char* a1 = cA + (size_t)(t + 1) * kstep;
;             const char* a2 = last ? nA : cA + (size_t)(t + 2) * kstep; const char* b2 = last ? nB : cB + (size_t)(t + 2) * kstep;
;     ...
;             PG8_LDA(At, 1, 1); PG8_STAGE(PG8_SB(1, 0), b3, voffB); PG8_STAGE(PG8_SB(1, 1), b3 + hstep, voffB); PG8_STAGE(PG8_SA(1, 0), a3, voffA);
;             PG8_WAIT_V(8); PG8_WAIT_L(0); PG8_BAR; PG8_MMA(1, 0, At, B0); PG8_MMA(1, 1, At, B1); PG8_BAR; PG8_SCHED;
	s_add_i32 s22, s33, s31
	v_lshl_add_u64 v[146:147], v[146:147], 0, s[6:7]
	s_mov_b32 m0, s22
	ds_read_b128 v[190:193], v153 offset:49152
	ds_read_b128 v[194:197], v153 offset:50176
	ds_read_b128 v[198:201], v153 offset:51200
	ds_read_b128 v[202:205], v153 offset:52224
	ds_read_b128 v[206:209], v153 offset:53248
	ds_read_b128 v[210:213], v153 offset:54272
	ds_read_b128 v[214:217], v153 offset:55296
	ds_read_b128 v[218:221], v153 offset:56320
	global_load_lds_dwordx4 v[146:147], off
	s_add_i32 m0, s22, 0x2000
	s_add_u32 s22, s26, 0xb0080
	v_lshl_add_u64 v[146:147], v[222:223], 0, s[6:7]
	s_addc_u32 s23, s27, 0
	s_add_i32 s26, s51, s31
	global_load_lds_dwordx4 v[146:147], off
	v_lshl_add_u64 v[146:147], s[22:23], 0, v[132:133]
	s_mov_b32 m0, s26
	s_nop 0
	global_load_lds_dwordx4 v[146:147], off
	v_lshl_add_u64 v[146:147], s[22:23], 0, v[136:137]
	s_add_i32 m0, s26, 0x2000
	s_nop 0
	global_load_lds_dwordx4 v[146:147], off
	v_lshl_add_u64 v[146:147], v[224:225], 0, s[6:7]
	s_mov_b32 m0, s39
	s_nop 0
	global_load_lds_dwordx4 v[146:147], off
	v_lshl_add_u64 v[146:147], v[226:227], 0, s[6:7]
	s_mov_b32 m0, s40
	s_nop 0
	global_load_lds_dwordx4 v[146:147], off
	s_waitcnt vmcnt(8)
	s_waitcnt lgkmcnt(0)
	s_barrier
	s_setprio 1
	s_waitcnt lgkmcnt(0)
	v_mfma_f32_16x16x32_bf16 v[62:65], v[154:157], v[190:193], v[62:65]
	v_mfma_f32_16x16x32_bf16 v[58:61], v[166:169], v[190:193], v[58:61]
	v_mfma_f32_16x16x32_bf16 v[54:57], v[154:157], v[198:201], v[54:57]
	v_mfma_f32_16x16x32_bf16 v[46:49], v[166:169], v[198:201], v[46:49]
	v_mfma_f32_16x16x32_bf16 v[38:41], v[154:157], v[206:209], v[38:41]
	v_mfma_f32_16x16x32_bf16 v[30:33], v[166:169], v[206:209], v[30:33]
	v_mfma_f32_16x16x32_bf16 v[22:25], v[154:157], v[214:217], v[22:25]
	v_mfma_f32_16x16x32_bf16 v[14:17], v[166:169], v[214:217], v[14:17]
	v_mfma_f32_16x16x32_bf16 v[62:65], v[158:161], v[194:197], v[62:65]
	v_mfma_f32_16x16x32_bf16 v[58:61], v[170:173], v[194:197], v[58:61]
	v_mfma_f32_16x16x32_bf16 v[54:57], v[158:161], v[202:205], v[54:57]
	v_mfma_f32_16x16x32_bf16 v[46:49], v[170:173], v[202:205], v[46:49]
	v_mfma_f32_16x16x32_bf16 v[38:41], v[158:161], v[210:213], v[38:41]
	v_mfma_f32_16x16x32_bf16 v[30:33], v[170:173], v[210:213], v[30:33]
	v_mfma_f32_16x16x32_bf16 v[22:25], v[158:161], v[218:221], v[22:25]
	v_mfma_f32_16x16x32_bf16 v[14:17], v[170:173], v[218:221], v[14:17]
	v_mfma_f32_16x16x32_bf16 v[50:53], v[174:177], v[190:193], v[50:53]
	v_mfma_f32_16x16x32_bf16 v[42:45], v[182:185], v[190:193], v[42:45]
	v_mfma_f32_16x16x32_bf16 v[34:37], v[174:177], v[198:201], v[34:37]
	v_mfma_f32_16x16x32_bf16 v[26:29], v[182:185], v[198:201], v[26:29]
	v_mfma_f32_16x16x32_bf16 v[18:21], v[174:177], v[206:209], v[18:21]
	v_mfma_f32_16x16x32_bf16 v[10:13], v[182:185], v[206:209], v[10:13]
	v_mfma_f32_16x16x32_bf16 v[6:9], v[174:177], v[214:217], v[6:9]
	v_mfma_f32_16x16x32_bf16 v[2:5], v[182:185], v[214:217], v[2:5]
	v_mfma_f32_16x16x32_bf16 v[50:53], v[178:181], v[194:197], v[50:53]
	v_mfma_f32_16x16x32_bf16 v[42:45], v[186:189], v[194:197], v[42:45]
	v_mfma_f32_16x16x32_bf16 v[34:37], v[178:181], v[202:205], v[34:37]
	v_mfma_f32_16x16x32_bf16 v[26:29], v[186:189], v[202:205], v[26:29]
	v_mfma_f32_16x16x32_bf16 v[18:21], v[178:181], v[210:213], v[18:21]
	v_mfma_f32_16x16x32_bf16 v[10:13], v[186:189], v[210:213], v[10:13]
	v_mfma_f32_16x16x32_bf16 v[6:9], v[178:181], v[218:221], v[6:9]
	v_mfma_f32_16x16x32_bf16 v[2:5], v[186:189], v[218:221], v[2:5]
	s_setprio 0
	s_barrier
	s_add_i32 s50, s50, 2
	s_add_u32 s48, s48, 0x100
	s_addc_u32 s49, s49, 0
	s_cmp_gt_u32 s50, 41
	s_mov_b64 s[22:23], s[24:25]
	s_cbranch_scc0 .LBB0_422
	s_and_b64 vcc, exec, s[18:19]
	s_cbranch_vccz .LBB0_425
	s_barrier

; #define PG8_STAGE(bufoff, gbase, voff) do { _Pragma("unroll") for (int _i = 0; _i < 2; ++_i) \
;         __builtin_amdgcn_global_load_lds((const unsigned*)((const char*)(gbase) + (voff)[_i]), (PG8_LAS unsigned*)(lds + (bufoff) + ldsw + _i * 8192), 16, 0, 0); } while (0)
; #define PG8_LDA(dst, b, h) do { _Pragma("unroll") for (int m = 0; m < 4; ++m) _Pragma("unroll") for (int k = 0; k < 2; ++k) dst[m][k] = *(const PG8_LAS bf16x8*)(lds + PG8_SA(b, h) + aoff + m * 2048 + k * 1024); } while (0)
; #define PG8_LDB(dst, b, h) do { _Pragma("unroll") for (int n = 0; n < 2; ++n) _Pragma("unroll") for (int k = 0; k < 2; ++k) dst[n][k] = *(const PG8_LAS bf16x8*)(lds + PG8_SB(b, h) + boff + n * 2048 + k * 1024); } while (0)
; #define PG8_MMA(ai, bj, At, Bt) do { __builtin_amdgcn_s_setprio(1); _Pragma("unroll") for (int m = 0; m < 4; ++m) _Pragma("unroll") for (int n = 0; n < 2; ++n) _Pragma("unroll") for (int k = 0; k < 2; ++k) \
;         acc[ai][bj][m][n] = __builtin_amdgcn_mfma_f32_16x16x32_bf16(Bt[n][k], At[m][k], acc[ai][bj][m][n], 0, 0, 0); __builtin_amdgcn_s_setprio(0); } while (0)
; #define PG8_WAIT_V(n) asm volatile("s_waitcnt vmcnt(" #n ")" ::: "memory")
; #define PG8_WAIT_L(n) asm volatile("s_waitcnt lgkmcnt(" #n ")" ::: "memory")
; #define PG8_BAR __builtin_amdgcn_s_barrier()
; #define PG8_SCHED __builtin_amdgcn_sched_barrier(0)
; template <class Epi, class Sched, bool ALIGN_EPI = false, bool SP2 = false>
; __device__ __forceinline__ void gemm_phase(PG8_LAS unsigned char* lds, const Gemm g, const Sched& S, const Epi& E) {
;     ...
;             PG8_LDB(B0, 0, 0); PG8_LDB(B1, 0, 1); PG8_SCHED; PG8_LDA(At, 0, 0); PG8_STAGE(PG8_SA(1, 1), a1 + hstep, voffA);
;             PG8_WAIT_V(8); PG8_WAIT_L(0); PG8_BAR; PG8_MMA(0, 0, At, B0); PG8_MMA(0, 1, At, B1); PG8_BAR; PG8_SCHED;
;             PG8_LDA(At, 0, 1); PG8_STAGE(PG8_SB(0, 0), b2, voffB); PG8_STAGE(PG8_SB(0, 1), b2 + hstep, voffB); PG8_STAGE(PG8_SA(0, 0), a2, voffA);
;             PG8_WAIT_V(8); PG8_WAIT_L(0); PG8_BAR; PG8_MMA(1, 0, At, B0); PG8_MMA(1, 1, At, B1); PG8_BAR; PG8_SCHED;
.LBB0_555:
	ds_read_b128 v[34:37], v237
	ds_read_b128 v[54:57], v237 offset:1024
	ds_read_b128 v[74:77], v237 offset:2048
	ds_read_b128 v[94:97], v237 offset:3072
	ds_read_b128 v[114:117], v238
	ds_read_b128 v[134:137], v238 offset:1024
	ds_read_b128 v[154:157], v238 offset:2048
	ds_read_b128 v[158:161], v238 offset:3072
	s_add_u32 s33, s8, 0xfffc0080
	s_addc_u32 s36, s9, -1
	s_cmp_eq_u32 s42, 12
	s_cselect_b32 s39, s7, s36
	s_cselect_b32 s38, s24, s33
	s_cselect_b32 s37, s27, s41
	s_cselect_b32 s36, s29, s40
	v_lshl_add_u64 v[224:225], s[8:9], 0, v[184:185]
	s_add_i32 m0, s51, 0xc000
	ds_read_b128 v[192:195], v239
	ds_read_b128 v[196:199], v239 offset:1024
	ds_read_b128 v[200:203], v239 offset:2048
	ds_read_b128 v[204:207], v239 offset:3072
	ds_read_b128 v[208:211], v239 offset:4096
	ds_read_b128 v[212:215], v239 offset:5120
	ds_read_b128 v[216:219], v239 offset:6144
	ds_read_b128 v[220:223], v239 offset:7168
	global_load_lds_dwordx4 v[224:225], off
	v_lshl_add_u64 v[224:225], s[8:9], 0, v[186:187]
	s_add_i32 m0, s51, 0xe000
	s_nop 0
	global_load_lds_dwordx4 v[224:225], off
	s_waitcnt vmcnt(8)
	s_waitcnt lgkmcnt(0)
	s_barrier
	s_setprio 1
	s_waitcnt lgkmcnt(0)
	v_mfma_f32_16x16x32_bf16 v[150:153], v[34:37], v[192:195], v[150:153]
	v_mfma_f32_16x16x32_bf16 v[146:149], v[74:77], v[192:195], v[146:149]
	v_mfma_f32_16x16x32_bf16 v[130:133], v[34:37], v[200:203], v[130:133]
	v_mfma_f32_16x16x32_bf16 v[126:129], v[74:77], v[200:203], v[126:129]
	v_mfma_f32_16x16x32_bf16 v[110:113], v[34:37], v[208:211], v[110:113]
	v_mfma_f32_16x16x32_bf16 v[106:109], v[74:77], v[208:211], v[106:109]
	v_mfma_f32_16x16x32_bf16 v[90:93], v[34:37], v[216:219], v[90:93]
	v_mfma_f32_16x16x32_bf16 v[86:89], v[74:77], v[216:219], v[86:89]
	v_mfma_f32_16x16x32_bf16 v[150:153], v[54:57], v[196:199], v[150:153]
	v_mfma_f32_16x16x32_bf16 v[146:149], v[94:97], v[196:199], v[146:149]
	v_mfma_f32_16x16x32_bf16 v[130:133], v[54:57], v[204:207], v[130:133]
	v_mfma_f32_16x16x32_bf16 v[126:129], v[94:97], v[204:207], v[126:129]
	v_mfma_f32_16x16x32_bf16 v[110:113], v[54:57], v[212:215], v[110:113]
	v_mfma_f32_16x16x32_bf16 v[106:109], v[94:97], v[212:215], v[106:109]
	v_mfma_f32_16x16x32_bf16 v[90:93], v[54:57], v[220:223], v[90:93]
	v_mfma_f32_16x16x32_bf16 v[86:89], v[94:97], v[220:223], v[86:89]
	v_mfma_f32_16x16x32_bf16 v[142:145], v[114:117], v[192:195], v[142:145]
	v_mfma_f32_16x16x32_bf16 v[138:141], v[154:157], v[192:195], v[138:141]
	v_mfma_f32_16x16x32_bf16 v[122:125], v[114:117], v[200:203], v[122:125]
	v_mfma_f32_16x16x32_bf16 v[118:121], v[154:157], v[200:203], v[118:121]
	v_mfma_f32_16x16x32_bf16 v[102:105], v[114:117], v[208:211], v[102:105]
	v_mfma_f32_16x16x32_bf16 v[98:101], v[154:157], v[208:211], v[98:101]
	v_mfma_f32_16x16x32_bf16 v[82:85], v[114:117], v[216:219], v[82:85]
	v_mfma_f32_16x16x32_bf16 v[78:81], v[154:157], v[216:219], v[78:81]
	v_mfma_f32_16x16x32_bf16 v[142:145], v[134:137], v[196:199], v[142:145]
	v_mfma_f32_16x16x32_bf16 v[138:141], v[158:161], v[196:199], v[138:141]
	v_mfma_f32_16x16x32_bf16 v[122:125], v[134:137], v[204:207], v[122:125]
	v_mfma_f32_16x16x32_bf16 v[118:121], v[158:161], v[204:207], v[118:121]
	v_mfma_f32_16x16x32_bf16 v[102:105], v[134:137], v[212:215], v[102:105]
	v_mfma_f32_16x16x32_bf16 v[98:101], v[158:161], v[212:215], v[98:101]
	v_mfma_f32_16x16x32_bf16 v[82:85], v[134:137], v[220:223], v[82:85]
	v_mfma_f32_16x16x32_bf16 v[78:81], v[158:161], v[220:223], v[78:81]
	s_setprio 0
	s_barrier
	s_add_i32 s33, s62, s50
	v_lshl_add_u64 v[224:225], s[36:37], 0, v[170:171]
	s_mov_b32 m0, s33
	ds_read_b128 v[192:195], v239 offset:16384
	ds_read_b128 v[196:199], v239 offset:17408
	ds_read_b128 v[200:203], v239 offset:18432
	ds_read_b128 v[204:207], v239 offset:19456
	ds_read_b128 v[208:211], v239 offset:20480
	ds_read_b128 v[212:215], v239 offset:21504
	ds_read_b128 v[216:219], v239 offset:22528
	ds_read_b128 v[220:223], v239 offset:23552
	global_load_lds_dwordx4 v[224:225], off
	s_add_i32 m0, s33, 0x2000
	s_add_u32 s44, s36, 0x40000
	v_lshl_add_u64 v[226:227], s[36:37], 0, v[174:175]
	s_addc_u32 s45, s37, 0
	s_add_i32 s33, s63, s50
	global_load_lds_dwordx4 v[226:227], off
	v_lshl_add_u64 v[228:229], s[44:45], 0, v[170:171]
	s_mov_b32 m0, s33
	v_lshl_add_u64 v[230:231], s[38:39], 0, v[172:173]
	global_load_lds_dwordx4 v[228:229], off
	v_lshl_add_u64 v[228:229], s[44:45], 0, v[174:175]
	s_add_i32 m0, s33, 0x2000
	s_nop 0
	global_load_lds_dwordx4 v[228:229], off
	v_lshl_add_u64 v[228:229], s[38:39], 0, v[168:169]
	s_mov_b32 m0, s51
	s_nop 0
	global_load_lds_dwordx4 v[228:229], off
	s_mov_b32 m0, s52
	s_nop 0
	global_load_lds_dwordx4 v[230:231], off
	s_waitcnt vmcnt(8)
	s_waitcnt lgkmcnt(0)
	s_barrier
; #define PG8_STAGE(bufoff, gbase, voff) do { _Pragma("unroll") for (int _i = 0; _i < 2; ++_i) \
;         __builtin_amdgcn_global_load_lds((const unsigned*)((const char*)(gbase) + (voff)[_i]), (PG8_LAS unsigned*)(lds + (bufoff) + ldsw + _i * 8192), 16, 0, 0); } while (0)
; #define PG8_LDA(dst, b, h) do { _Pragma("unroll") for (int m = 0; m < 4; ++m) _Pragma("unroll") for (int k = 0; k < 2; ++k) dst[m][k] = *(const PG8_LAS bf16x8*)(lds + PG8_SA(b, h) + aoff + m * 2048 + k * 1024); } while (0)
; #define PG8_LDB(dst, b, h) do { _Pragma("unroll") for (int n = 0; n < 2; ++n) _Pragma("unroll") for (int k = 0; k < 2; ++k) dst[n][k] = *(const PG8_LAS bf16x8*)(lds + PG8_SB(b, h) + boff + n * 2048 + k * 1024); } while (0)
; #define PG8_MMA(ai, bj, At, Bt) do { __builtin_amdgcn_s_setprio(1); _Pragma("unroll") for (int m = 0; m < 4; ++m) _Pragma("unroll") for (int n = 0; n < 2; ++n) _Pragma("unroll") for (int k = 0; k < 2; ++k) \
;         acc[ai][bj][m][n] = __builtin_amdgcn_mfma_f32_16x16x32_bf16(Bt[n][k], At[m][k], acc[ai][bj][m][n], 0, 0, 0); __builtin_amdgcn_s_setprio(0); } while (0)
; #define PG8_WAIT_V(n) asm volatile("s_waitcnt vmcnt(" #n ")" ::: "memory")
; #define PG8_WAIT_L(n) asm volatile("s_waitcnt lgkmcnt(" #n ")" ::: "memory")
; #define PG8_BAR __builtin_amdgcn_s_barrier()
; #define PG8_SCHED __builtin_amdgcn_sched_barrier(0)
; template <class Epi, class Sched, bool ALIGN_EPI = false, bool SP2 = false>
; __device__ __forceinline__ void gemm_phase(PG8_LAS unsigned char* lds, const Gemm g, const Sched& S, const Epi& E) {
;     ...
;             PG8_WAIT_V(8); PG8_WAIT_L(0); PG8_BAR; PG8_MMA(1, 0, At, B0); PG8_MMA(1, 1, At, B1); PG8_BAR; PG8_SCHED;
;             PG8_LDB(B0, 1, 0); PG8_LDB(B1, 1, 1); PG8_SCHED; PG8_LDA(At, 1, 0); PG8_STAGE(PG8_SA(0, 1), a2 + hstep, voffA);
;             PG8_WAIT_V(8); PG8_WAIT_L(0); PG8_BAR; PG8_MMA(0, 0, At, B0); PG8_MMA(0, 1, At, B1); PG8_BAR; PG8_SCHED;
	s_setprio 1
	s_waitcnt lgkmcnt(0)
	v_mfma_f32_16x16x32_bf16 v[70:73], v[34:37], v[192:195], v[70:73]
	v_mfma_f32_16x16x32_bf16 v[66:69], v[74:77], v[192:195], v[66:69]
	v_mfma_f32_16x16x32_bf16 v[50:53], v[34:37], v[200:203], v[50:53]
	v_mfma_f32_16x16x32_bf16 v[46:49], v[74:77], v[200:203], v[46:49]
	v_mfma_f32_16x16x32_bf16 v[30:33], v[34:37], v[208:211], v[30:33]
	v_mfma_f32_16x16x32_bf16 v[26:29], v[74:77], v[208:211], v[26:29]
	v_mfma_f32_16x16x32_bf16 v[14:17], v[34:37], v[216:219], v[14:17]
	v_mfma_f32_16x16x32_bf16 v[10:13], v[74:77], v[216:219], v[10:13]
	v_mfma_f32_16x16x32_bf16 v[70:73], v[54:57], v[196:199], v[70:73]
	v_mfma_f32_16x16x32_bf16 v[66:69], v[94:97], v[196:199], v[66:69]
	v_mfma_f32_16x16x32_bf16 v[50:53], v[54:57], v[204:207], v[50:53]
	v_mfma_f32_16x16x32_bf16 v[46:49], v[94:97], v[204:207], v[46:49]
	v_mfma_f32_16x16x32_bf16 v[30:33], v[54:57], v[212:215], v[30:33]
	v_mfma_f32_16x16x32_bf16 v[26:29], v[94:97], v[212:215], v[26:29]
	v_mfma_f32_16x16x32_bf16 v[14:17], v[54:57], v[220:223], v[14:17]
	v_mfma_f32_16x16x32_bf16 v[10:13], v[94:97], v[220:223], v[10:13]
	v_mfma_f32_16x16x32_bf16 v[42:45], v[114:117], v[200:203], v[42:45]
	v_mfma_f32_16x16x32_bf16 v[38:41], v[154:157], v[200:203], v[38:41]
	v_mfma_f32_16x16x32_bf16 v[22:25], v[114:117], v[208:211], v[22:25]
	v_mfma_f32_16x16x32_bf16 v[18:21], v[154:157], v[208:211], v[18:21]
	v_mfma_f32_16x16x32_bf16 v[6:9], v[114:117], v[216:219], v[6:9]
	v_mfma_f32_16x16x32_bf16 v[2:5], v[154:157], v[216:219], v[2:5]
	v_mfma_f32_16x16x32_bf16 v[34:37], v[114:117], v[192:195], v[62:65]
	v_mfma_f32_16x16x32_bf16 v[54:57], v[154:157], v[192:195], v[58:61]
	v_mfma_f32_16x16x32_bf16 v[42:45], v[134:137], v[204:207], v[42:45]
	v_mfma_f32_16x16x32_bf16 v[38:41], v[158:161], v[204:207], v[38:41]
	v_mfma_f32_16x16x32_bf16 v[22:25], v[134:137], v[212:215], v[22:25]
	v_mfma_f32_16x16x32_bf16 v[18:21], v[158:161], v[212:215], v[18:21]
	v_mfma_f32_16x16x32_bf16 v[6:9], v[134:137], v[220:223], v[6:9]
	v_mfma_f32_16x16x32_bf16 v[2:5], v[158:161], v[220:223], v[2:5]
	v_mfma_f32_16x16x32_bf16 v[34:37], v[134:137], v[196:199], v[34:37]
	v_mfma_f32_16x16x32_bf16 v[54:57], v[158:161], v[196:199], v[54:57]
	s_setprio 0
	s_barrier
	s_add_i32 s33, 0, 0x18000
	s_add_i32 s43, 0, 0x1c000
	v_add_u32_e32 v94, s33, v167
	v_add_u32_e32 v158, s43, v167
	ds_read_b128 v[58:61], v94
	ds_read_b128 v[62:65], v94 offset:1024
	ds_read_b128 v[74:77], v94 offset:2048
	ds_read_b128 v[94:97], v94 offset:3072
	ds_read_b128 v[114:117], v158
	ds_read_b128 v[134:137], v158 offset:1024
	ds_read_b128 v[154:157], v158 offset:2048
	ds_read_b128 v[158:161], v158 offset:3072
	s_add_u32 s38, s38, 0x40000
	s_addc_u32 s39, s39, 0
	s_mov_b32 m0, s53
	v_lshl_add_u64 v[232:233], s[38:39], 0, v[168:169]
	ds_read_b128 v[192:195], v239 offset:32768
	ds_read_b128 v[196:199], v239 offset:33792
	ds_read_b128 v[200:203], v239 offset:34816
	ds_read_b128 v[204:207], v239 offset:35840
	ds_read_b128 v[208:211], v239 offset:36864
	ds_read_b128 v[212:215], v239 offset:37888
	ds_read_b128 v[216:219], v239 offset:38912
	ds_read_b128 v[220:223], v239 offset:39936
	global_load_lds_dwordx4 v[232:233], off
	v_lshl_add_u64 v[232:233], s[38:39], 0, v[172:173]
	s_mov_b32 m0, s54
	s_nop 0
	global_load_lds_dwordx4 v[232:233], off
	s_waitcnt vmcnt(8)
	s_waitcnt lgkmcnt(0)
	s_barrier
	s_setprio 1
	s_waitcnt lgkmcnt(0)
	v_mfma_f32_16x16x32_bf16 v[150:153], v[58:61], v[192:195], v[150:153]
	v_mfma_f32_16x16x32_bf16 v[146:149], v[74:77], v[192:195], v[146:149]
	v_mfma_f32_16x16x32_bf16 v[130:133], v[58:61], v[200:203], v[130:133]
	v_mfma_f32_16x16x32_bf16 v[126:129], v[74:77], v[200:203], v[126:129]
	v_mfma_f32_16x16x32_bf16 v[110:113], v[58:61], v[208:211], v[110:113]
	v_mfma_f32_16x16x32_bf16 v[106:109], v[74:77], v[208:211], v[106:109]
	v_mfma_f32_16x16x32_bf16 v[90:93], v[58:61], v[216:219], v[90:93]
	v_mfma_f32_16x16x32_bf16 v[86:89], v[74:77], v[216:219], v[86:89]
	v_mfma_f32_16x16x32_bf16 v[150:153], v[62:65], v[196:199], v[150:153]
	v_mfma_f32_16x16x32_bf16 v[146:149], v[94:97], v[196:199], v[146:149]
	v_mfma_f32_16x16x32_bf16 v[130:133], v[62:65], v[204:207], v[130:133]
	v_mfma_f32_16x16x32_bf16 v[126:129], v[94:97], v[204:207], v[126:129]
	v_mfma_f32_16x16x32_bf16 v[110:113], v[62:65], v[212:215], v[110:113]
	v_mfma_f32_16x16x32_bf16 v[106:109], v[94:97], v[212:215], v[106:109]
	v_mfma_f32_16x16x32_bf16 v[90:93], v[62:65], v[220:223], v[90:93]
	v_mfma_f32_16x16x32_bf16 v[86:89], v[94:97], v[220:223], v[86:89]
	v_mfma_f32_16x16x32_bf16 v[142:145], v[114:117], v[192:195], v[142:145]
	v_mfma_f32_16x16x32_bf16 v[138:141], v[154:157], v[192:195], v[138:141]
	v_mfma_f32_16x16x32_bf16 v[122:125], v[114:117], v[200:203], v[122:125]
	v_mfma_f32_16x16x32_bf16 v[118:121], v[154:157], v[200:203], v[118:121]
	v_mfma_f32_16x16x32_bf16 v[102:105], v[114:117], v[208:211], v[102:105]
	v_mfma_f32_16x16x32_bf16 v[98:101], v[154:157], v[208:211], v[98:101]
	v_mfma_f32_16x16x32_bf16 v[82:85], v[114:117], v[216:219], v[82:85]
	v_mfma_f32_16x16x32_bf16 v[78:81], v[154:157], v[216:219], v[78:81]
	v_mfma_f32_16x16x32_bf16 v[142:145], v[134:137], v[196:199], v[142:145]
	v_mfma_f32_16x16x32_bf16 v[138:141], v[158:161], v[196:199], v[138:141]
	v_mfma_f32_16x16x32_bf16 v[122:125], v[134:137], v[204:207], v[122:125]
	v_mfma_f32_16x16x32_bf16 v[118:121], v[158:161], v[204:207], v[118:121]
	v_mfma_f32_16x16x32_bf16 v[102:105], v[134:137], v[212:215], v[102:105]
	v_mfma_f32_16x16x32_bf16 v[98:101], v[158:161], v[212:215], v[98:101]
	v_mfma_f32_16x16x32_bf16 v[82:85], v[134:137], v[220:223], v[82:85]
	v_mfma_f32_16x16x32_bf16 v[78:81], v[158:161], v[220:223], v[78:81]
	s_setprio 0
	s_barrier
; #define PG8_STAGE(bufoff, gbase, voff) do { _Pragma("unroll") for (int _i = 0; _i < 2; ++_i) \
;         __builtin_amdgcn_global_load_lds((const unsigned*)((const char*)(gbase) + (voff)[_i]), (PG8_LAS unsigned*)(lds + (bufoff) + ldsw + _i * 8192), 16, 0, 0); } while (0)
; #define PG8_LDA(dst, b, h) do { _Pragma("unroll") for (int m = 0; m < 4; ++m) _Pragma("unroll") for (int k = 0; k < 2; ++k) dst[m][k] = *(const PG8_LAS bf16x8*)(lds + PG8_SA(b, h) + aoff + m * 2048 + k * 1024); } while (0)
; #define PG8_MMA(ai, bj, At, Bt) do { __builtin_amdgcn_s_setprio(1); _Pragma("unroll") for (int m = 0; m < 4; ++m) _Pragma("unroll") for (int n = 0; n < 2; ++n) _Pragma("unroll") for (int k = 0; k < 2; ++k) \
;         acc[ai][bj][m][n] = __builtin_amdgcn_mfma_f32_16x16x32_bf16(Bt[n][k], At[m][k], acc[ai][bj][m][n], 0, 0, 0); __builtin_amdgcn_s_setprio(0); } while (0)
; #define PG8_WAIT_V(n) asm volatile("s_waitcnt vmcnt(" #n ")" ::: "memory")
; #define PG8_WAIT_L(n) asm volatile("s_waitcnt lgkmcnt(" #n ")" ::: "memory")
; #define PG8_BAR __builtin_amdgcn_s_barrier()
; #define PG8_SCHED __builtin_amdgcn_sched_barrier(0)
; template <class Epi, class Sched, bool ALIGN_EPI = false, bool SP2 = false>
; __device__ __forceinline__ void gemm_phase(PG8_LAS unsigned char* lds, const Gemm g, const Sched& S, const Epi& E) {
;     ...
;         for (int t = 0; t < nt; t += 2) {
;             const bool last = (t == nt - 2);
;             const char* a1 = cA + (size_t)(t + 1) * kstep;
;             const char* a2 = last ? nA : cA + (size_t)(t + 2) * kstep; const char* b2 = last ? nB : cB + (size_t)(t + 2) * kstep;
;     ...
;             PG8_LDA(At, 1, 1); PG8_STAGE(PG8_SB(1, 0), b3, voffB); PG8_STAGE(PG8_SB(1, 1), b3 + hstep, voffB); PG8_STAGE(PG8_SA(1, 0), a3, voffA);
;             PG8_WAIT_V(8); PG8_WAIT_L(0); PG8_BAR; PG8_MMA(1, 0, At, B0); PG8_MMA(1, 1, At, B1); PG8_BAR; PG8_SCHED;
	s_add_i32 s33, s33, s50
	v_lshl_add_u64 v[224:225], v[224:225], 0, s[20:21]
	s_mov_b32 m0, s33
	ds_read_b128 v[192:195], v239 offset:49152
	ds_read_b128 v[196:199], v239 offset:50176
	ds_read_b128 v[200:203], v239 offset:51200
	ds_read_b128 v[204:207], v239 offset:52224
	ds_read_b128 v[208:211], v239 offset:53248
	ds_read_b128 v[212:215], v239 offset:54272
	ds_read_b128 v[216:219], v239 offset:55296
	ds_read_b128 v[220:223], v239 offset:56320
	global_load_lds_dwordx4 v[224:225], off
	s_add_i32 m0, s33, 0x2000
	s_add_u32 s36, s36, 0x40080
	v_lshl_add_u64 v[224:225], v[226:227], 0, s[20:21]
	s_addc_u32 s37, s37, 0
	s_add_i32 s33, s43, s50
	global_load_lds_dwordx4 v[224:225], off
	v_lshl_add_u64 v[224:225], s[36:37], 0, v[170:171]
	s_mov_b32 m0, s33
	s_nop 0
	global_load_lds_dwordx4 v[224:225], off
	v_lshl_add_u64 v[224:225], s[36:37], 0, v[174:175]
	s_add_i32 m0, s33, 0x2000
	s_nop 0
	global_load_lds_dwordx4 v[224:225], off
	v_lshl_add_u64 v[224:225], v[228:229], 0, s[20:21]
	s_mov_b32 m0, s57
	s_nop 0
	global_load_lds_dwordx4 v[224:225], off
	v_lshl_add_u64 v[224:225], v[230:231], 0, s[20:21]
	s_mov_b32 m0, s58
	s_nop 0
	global_load_lds_dwordx4 v[224:225], off
	s_waitcnt vmcnt(8)
	s_waitcnt lgkmcnt(0)
	s_barrier
	s_setprio 1
	s_waitcnt lgkmcnt(0)
	v_mfma_f32_16x16x32_bf16 v[70:73], v[58:61], v[192:195], v[70:73]
	v_mfma_f32_16x16x32_bf16 v[66:69], v[74:77], v[192:195], v[66:69]
	v_mfma_f32_16x16x32_bf16 v[50:53], v[58:61], v[200:203], v[50:53]
	v_mfma_f32_16x16x32_bf16 v[46:49], v[74:77], v[200:203], v[46:49]
	v_mfma_f32_16x16x32_bf16 v[30:33], v[58:61], v[208:211], v[30:33]
	v_mfma_f32_16x16x32_bf16 v[26:29], v[74:77], v[208:211], v[26:29]
	v_mfma_f32_16x16x32_bf16 v[14:17], v[58:61], v[216:219], v[14:17]
	v_mfma_f32_16x16x32_bf16 v[10:13], v[74:77], v[216:219], v[10:13]
	v_mfma_f32_16x16x32_bf16 v[70:73], v[62:65], v[196:199], v[70:73]
	v_mfma_f32_16x16x32_bf16 v[66:69], v[94:97], v[196:199], v[66:69]
	v_mfma_f32_16x16x32_bf16 v[50:53], v[62:65], v[204:207], v[50:53]
	v_mfma_f32_16x16x32_bf16 v[46:49], v[94:97], v[204:207], v[46:49]
	v_mfma_f32_16x16x32_bf16 v[30:33], v[62:65], v[212:215], v[30:33]
	v_mfma_f32_16x16x32_bf16 v[26:29], v[94:97], v[212:215], v[26:29]
	v_mfma_f32_16x16x32_bf16 v[14:17], v[62:65], v[220:223], v[14:17]
	v_mfma_f32_16x16x32_bf16 v[10:13], v[94:97], v[220:223], v[10:13]
	v_mfma_f32_16x16x32_bf16 v[34:37], v[114:117], v[192:195], v[34:37]
	v_mfma_f32_16x16x32_bf16 v[62:65], v[134:137], v[196:199], v[34:37]
	v_mfma_f32_16x16x32_bf16 v[34:37], v[154:157], v[192:195], v[54:57]
	v_mfma_f32_16x16x32_bf16 v[58:61], v[158:161], v[196:199], v[34:37]
	v_mfma_f32_16x16x32_bf16 v[34:37], v[114:117], v[200:203], v[42:45]
	v_mfma_f32_16x16x32_bf16 v[42:45], v[134:137], v[204:207], v[34:37]
	v_mfma_f32_16x16x32_bf16 v[34:37], v[154:157], v[200:203], v[38:41]
	v_mfma_f32_16x16x32_bf16 v[22:25], v[114:117], v[208:211], v[22:25]
	v_mfma_f32_16x16x32_bf16 v[18:21], v[154:157], v[208:211], v[18:21]
	v_mfma_f32_16x16x32_bf16 v[6:9], v[114:117], v[216:219], v[6:9]
	v_mfma_f32_16x16x32_bf16 v[2:5], v[154:157], v[216:219], v[2:5]
	v_mfma_f32_16x16x32_bf16 v[38:41], v[158:161], v[204:207], v[34:37]
	v_mfma_f32_16x16x32_bf16 v[22:25], v[134:137], v[212:215], v[22:25]
	v_mfma_f32_16x16x32_bf16 v[18:21], v[158:161], v[212:215], v[18:21]
	v_mfma_f32_16x16x32_bf16 v[6:9], v[134:137], v[220:223], v[6:9]
	v_mfma_f32_16x16x32_bf16 v[2:5], v[158:161], v[220:223], v[2:5]
	s_setprio 0
	s_barrier
	s_add_i32 s42, s42, 2
	s_add_u32 s8, s8, 0x100
	s_addc_u32 s9, s9, 0
	s_add_u32 s40, s40, 0x100
	s_addc_u32 s41, s41, 0
	s_cmp_gt_u32 s42, 13
	s_cbranch_scc0 .LBB0_555
	s_and_b64 vcc, exec, s[22:23]
	s_cbranch_vccz .LBB0_558
	s_barrier

; #define PG8_STAGE(bufoff, gbase, voff) do { _Pragma("unroll") for (int _i = 0; _i < 2; ++_i) \
;         __builtin_amdgcn_global_load_lds((const unsigned*)((const char*)(gbase) + (voff)[_i]), (PG8_LAS unsigned*)(lds + (bufoff) + ldsw + _i * 8192), 16, 0, 0); } while (0)
; #define PG8_LDA(dst, b, h) do { _Pragma("unroll") for (int m = 0; m < 4; ++m) _Pragma("unroll") for (int k = 0; k < 2; ++k) dst[m][k] = *(const PG8_LAS bf16x8*)(lds + PG8_SA(b, h) + aoff + m * 2048 + k * 1024); } while (0)
; #define PG8_LDB(dst, b, h) do { _Pragma("unroll") for (int n = 0; n < 2; ++n) _Pragma("unroll") for (int k = 0; k < 2; ++k) dst[n][k] = *(const PG8_LAS bf16x8*)(lds + PG8_SB(b, h) + boff + n * 2048 + k * 1024); } while (0)
; #define PG8_MMA(ai, bj, At, Bt) do { __builtin_amdgcn_s_setprio(1); _Pragma("unroll") for (int m = 0; m < 4; ++m) _Pragma("unroll") for (int n = 0; n < 2; ++n) _Pragma("unroll") for (int k = 0; k < 2; ++k) \
;         acc[ai][bj][m][n] = __builtin_amdgcn_mfma_f32_16x16x32_bf16(Bt[n][k], At[m][k], acc[ai][bj][m][n], 0, 0, 0); __builtin_amdgcn_s_setprio(0); } while (0)
; #define PG8_WAIT_V(n) asm volatile("s_waitcnt vmcnt(" #n ")" ::: "memory")
; #define PG8_WAIT_L(n) asm volatile("s_waitcnt lgkmcnt(" #n ")" ::: "memory")
; #define PG8_BAR __builtin_amdgcn_s_barrier()
; #define PG8_SCHED __builtin_amdgcn_sched_barrier(0)
; template <class Epi, class Sched, bool ALIGN_EPI = false, bool SP2 = false>
; __device__ __forceinline__ void gemm_phase(PG8_LAS unsigned char* lds, const Gemm g, const Sched& S, const Epi& E) {
;     ...
;             PG8_LDB(B0, 0, 0); PG8_LDB(B1, 0, 1); PG8_SCHED; PG8_LDA(At, 0, 0); PG8_STAGE(PG8_SA(1, 1), a1 + hstep, voffA);
;             PG8_WAIT_V(8); PG8_WAIT_L(0); PG8_BAR; PG8_MMA(0, 0, At, B0); PG8_MMA(0, 1, At, B1); PG8_BAR; PG8_SCHED;
;             PG8_LDA(At, 0, 1); PG8_STAGE(PG8_SB(0, 0), b2, voffB); PG8_STAGE(PG8_SB(0, 1), b2 + hstep, voffB); PG8_STAGE(PG8_SA(0, 0), a2, voffA);
;             PG8_WAIT_V(8); PG8_WAIT_L(0); PG8_BAR; PG8_MMA(1, 0, At, B0); PG8_MMA(1, 1, At, B1); PG8_BAR; PG8_SCHED;
.LBB0_1423:
	ds_read_b128 v[156:159], v153
	ds_read_b128 v[168:171], v153 offset:1024
	ds_read_b128 v[172:175], v153 offset:2048
	ds_read_b128 v[176:179], v153 offset:3072
	ds_read_b128 v[180:183], v154
	ds_read_b128 v[192:195], v154 offset:1024
	ds_read_b128 v[196:199], v154 offset:2048
	ds_read_b128 v[200:203], v154 offset:3072
	s_add_u32 s24, s22, 0xfffc0080
	s_addc_u32 s25, s23, -1
	s_cmp_eq_u32 s46, 12
	s_cselect_b32 s27, s15, s25
	s_cselect_b32 s26, s42, s24
	s_cselect_b32 s25, s13, s45
	s_cselect_b32 s24, s43, s44
	v_lshl_add_u64 v[150:151], s[22:23], 0, v[142:143]
	s_add_i32 m0, s21, 0xc000
	ds_read_b128 v[204:207], v155
	ds_read_b128 v[208:211], v155 offset:1024
	ds_read_b128 v[212:215], v155 offset:2048
	ds_read_b128 v[216:219], v155 offset:3072
	ds_read_b128 v[220:223], v155 offset:4096
	ds_read_b128 v[224:227], v155 offset:5120
	ds_read_b128 v[228:231], v155 offset:6144
	ds_read_b128 v[232:235], v155 offset:7168
	global_load_lds_dwordx4 v[150:151], off
	v_lshl_add_u64 v[150:151], s[22:23], 0, v[144:145]
	s_add_i32 m0, s21, 0xe000
	s_nop 0
	global_load_lds_dwordx4 v[150:151], off
	s_waitcnt vmcnt(8)
	s_waitcnt lgkmcnt(0)
	s_barrier
	s_setprio 1
	s_waitcnt lgkmcnt(0)
	v_mfma_f32_16x16x32_bf16 v[126:129], v[156:159], v[204:207], v[126:129]
	v_mfma_f32_16x16x32_bf16 v[122:125], v[172:175], v[204:207], v[122:125]
	v_mfma_f32_16x16x32_bf16 v[118:121], v[156:159], v[212:215], v[118:121]
	v_mfma_f32_16x16x32_bf16 v[110:113], v[172:175], v[212:215], v[110:113]
	v_mfma_f32_16x16x32_bf16 v[102:105], v[156:159], v[220:223], v[102:105]
	v_mfma_f32_16x16x32_bf16 v[94:97], v[172:175], v[220:223], v[94:97]
	v_mfma_f32_16x16x32_bf16 v[82:85], v[156:159], v[228:231], v[82:85]
	v_mfma_f32_16x16x32_bf16 v[74:77], v[172:175], v[228:231], v[74:77]
	v_mfma_f32_16x16x32_bf16 v[126:129], v[168:171], v[208:211], v[126:129]
	v_mfma_f32_16x16x32_bf16 v[122:125], v[176:179], v[208:211], v[122:125]
	v_mfma_f32_16x16x32_bf16 v[118:121], v[168:171], v[216:219], v[118:121]
	v_mfma_f32_16x16x32_bf16 v[110:113], v[176:179], v[216:219], v[110:113]
	v_mfma_f32_16x16x32_bf16 v[102:105], v[168:171], v[224:227], v[102:105]
	v_mfma_f32_16x16x32_bf16 v[94:97], v[176:179], v[224:227], v[94:97]
	v_mfma_f32_16x16x32_bf16 v[82:85], v[168:171], v[232:235], v[82:85]
	v_mfma_f32_16x16x32_bf16 v[74:77], v[176:179], v[232:235], v[74:77]
	v_mfma_f32_16x16x32_bf16 v[114:117], v[180:183], v[204:207], v[114:117]
	v_mfma_f32_16x16x32_bf16 v[106:109], v[196:199], v[204:207], v[106:109]
	v_mfma_f32_16x16x32_bf16 v[98:101], v[180:183], v[212:215], v[98:101]
	v_mfma_f32_16x16x32_bf16 v[90:93], v[196:199], v[212:215], v[90:93]
	v_mfma_f32_16x16x32_bf16 v[86:89], v[180:183], v[220:223], v[86:89]
	v_mfma_f32_16x16x32_bf16 v[78:81], v[196:199], v[220:223], v[78:81]
	v_mfma_f32_16x16x32_bf16 v[70:73], v[180:183], v[228:231], v[70:73]
	v_mfma_f32_16x16x32_bf16 v[66:69], v[196:199], v[228:231], v[66:69]
	v_mfma_f32_16x16x32_bf16 v[114:117], v[192:195], v[208:211], v[114:117]
	v_mfma_f32_16x16x32_bf16 v[106:109], v[200:203], v[208:211], v[106:109]
	v_mfma_f32_16x16x32_bf16 v[98:101], v[192:195], v[216:219], v[98:101]
	v_mfma_f32_16x16x32_bf16 v[90:93], v[200:203], v[216:219], v[90:93]
	v_mfma_f32_16x16x32_bf16 v[86:89], v[192:195], v[224:227], v[86:89]
	v_mfma_f32_16x16x32_bf16 v[78:81], v[200:203], v[224:227], v[78:81]
	v_mfma_f32_16x16x32_bf16 v[70:73], v[192:195], v[232:235], v[70:73]
	v_mfma_f32_16x16x32_bf16 v[66:69], v[200:203], v[232:235], v[66:69]
	s_setprio 0
	s_barrier
	s_add_i32 s33, s37, s29
	v_lshl_add_u64 v[150:151], s[24:25], 0, v[136:137]
	s_mov_b32 m0, s33
	ds_read_b128 v[204:207], v155 offset:16384
	ds_read_b128 v[208:211], v155 offset:17408
	ds_read_b128 v[212:215], v155 offset:18432
	ds_read_b128 v[216:219], v155 offset:19456
	ds_read_b128 v[220:223], v155 offset:20480
	ds_read_b128 v[224:227], v155 offset:21504
	ds_read_b128 v[228:231], v155 offset:22528
	ds_read_b128 v[232:235], v155 offset:23552
	global_load_lds_dwordx4 v[150:151], off
	s_add_i32 m0, s33, 0x2000
	s_add_u32 s48, s24, 0x40000
	v_lshl_add_u64 v[160:161], s[24:25], 0, v[140:141]
	s_addc_u32 s49, s25, 0
	s_add_i32 s33, s38, s29
	global_load_lds_dwordx4 v[160:161], off
	v_lshl_add_u64 v[184:185], s[48:49], 0, v[136:137]
	s_mov_b32 m0, s33
	v_lshl_add_u64 v[238:239], s[26:27], 0, v[138:139]
	global_load_lds_dwordx4 v[184:185], off
	v_lshl_add_u64 v[184:185], s[48:49], 0, v[140:141]
	s_add_i32 m0, s33, 0x2000
	s_nop 0
	global_load_lds_dwordx4 v[184:185], off
	v_lshl_add_u64 v[184:185], s[26:27], 0, v[134:135]
	s_mov_b32 m0, s21
	s_nop 0
	global_load_lds_dwordx4 v[184:185], off
	s_mov_b32 m0, s30
	s_nop 0
	global_load_lds_dwordx4 v[238:239], off
	s_waitcnt vmcnt(8)
	s_waitcnt lgkmcnt(0)
	s_barrier
; #define PG8_STAGE(bufoff, gbase, voff) do { _Pragma("unroll") for (int _i = 0; _i < 2; ++_i) \
;         __builtin_amdgcn_global_load_lds((const unsigned*)((const char*)(gbase) + (voff)[_i]), (PG8_LAS unsigned*)(lds + (bufoff) + ldsw + _i * 8192), 16, 0, 0); } while (0)
; #define PG8_LDA(dst, b, h) do { _Pragma("unroll") for (int m = 0; m < 4; ++m) _Pragma("unroll") for (int k = 0; k < 2; ++k) dst[m][k] = *(const PG8_LAS bf16x8*)(lds + PG8_SA(b, h) + aoff + m * 2048 + k * 1024); } while (0)
; #define PG8_LDB(dst, b, h) do { _Pragma("unroll") for (int n = 0; n < 2; ++n) _Pragma("unroll") for (int k = 0; k < 2; ++k) dst[n][k] = *(const PG8_LAS bf16x8*)(lds + PG8_SB(b, h) + boff + n * 2048 + k * 1024); } while (0)
; #define PG8_MMA(ai, bj, At, Bt) do { __builtin_amdgcn_s_setprio(1); _Pragma("unroll") for (int m = 0; m < 4; ++m) _Pragma("unroll") for (int n = 0; n < 2; ++n) _Pragma("unroll") for (int k = 0; k < 2; ++k) \
;         acc[ai][bj][m][n] = __builtin_amdgcn_mfma_f32_16x16x32_bf16(Bt[n][k], At[m][k], acc[ai][bj][m][n], 0, 0, 0); __builtin_amdgcn_s_setprio(0); } while (0)
; #define PG8_WAIT_V(n) asm volatile("s_waitcnt vmcnt(" #n ")" ::: "memory")
; #define PG8_WAIT_L(n) asm volatile("s_waitcnt lgkmcnt(" #n ")" ::: "memory")
; #define PG8_BAR __builtin_amdgcn_s_barrier()
; #define PG8_SCHED __builtin_amdgcn_sched_barrier(0)
; template <class Epi, class Sched, bool ALIGN_EPI = false, bool SP2 = false>
; __device__ __forceinline__ void gemm_phase(PG8_LAS unsigned char* lds, const Gemm g, const Sched& S, const Epi& E) {
;     ...
;             PG8_WAIT_V(8); PG8_WAIT_L(0); PG8_BAR; PG8_MMA(1, 0, At, B0); PG8_MMA(1, 1, At, B1); PG8_BAR; PG8_SCHED;
;             PG8_LDB(B0, 1, 0); PG8_LDB(B1, 1, 1); PG8_SCHED; PG8_LDA(At, 1, 0); PG8_STAGE(PG8_SA(0, 1), a2 + hstep, voffA);
;             PG8_WAIT_V(8); PG8_WAIT_L(0); PG8_BAR; PG8_MMA(0, 0, At, B0); PG8_MMA(0, 1, At, B1); PG8_BAR; PG8_SCHED;
	s_setprio 1
	s_waitcnt lgkmcnt(0)
	v_mfma_f32_16x16x32_bf16 v[62:65], v[156:159], v[204:207], v[62:65]
	v_mfma_f32_16x16x32_bf16 v[58:61], v[172:175], v[204:207], v[58:61]
	v_mfma_f32_16x16x32_bf16 v[54:57], v[156:159], v[212:215], v[54:57]
	v_mfma_f32_16x16x32_bf16 v[46:49], v[172:175], v[212:215], v[46:49]
	v_mfma_f32_16x16x32_bf16 v[38:41], v[156:159], v[220:223], v[38:41]
	v_mfma_f32_16x16x32_bf16 v[30:33], v[172:175], v[220:223], v[30:33]
	v_mfma_f32_16x16x32_bf16 v[22:25], v[156:159], v[228:231], v[22:25]
	v_mfma_f32_16x16x32_bf16 v[14:17], v[172:175], v[228:231], v[14:17]
	v_mfma_f32_16x16x32_bf16 v[62:65], v[168:171], v[208:211], v[62:65]
	v_mfma_f32_16x16x32_bf16 v[58:61], v[176:179], v[208:211], v[58:61]
	v_mfma_f32_16x16x32_bf16 v[54:57], v[168:171], v[216:219], v[54:57]
	v_mfma_f32_16x16x32_bf16 v[46:49], v[176:179], v[216:219], v[46:49]
	v_mfma_f32_16x16x32_bf16 v[38:41], v[168:171], v[224:227], v[38:41]
	v_mfma_f32_16x16x32_bf16 v[30:33], v[176:179], v[224:227], v[30:33]
	v_mfma_f32_16x16x32_bf16 v[22:25], v[168:171], v[232:235], v[22:25]
	v_mfma_f32_16x16x32_bf16 v[14:17], v[176:179], v[232:235], v[14:17]
	v_mfma_f32_16x16x32_bf16 v[50:53], v[180:183], v[204:207], v[50:53]
	v_mfma_f32_16x16x32_bf16 v[42:45], v[196:199], v[204:207], v[42:45]
	v_mfma_f32_16x16x32_bf16 v[34:37], v[180:183], v[212:215], v[34:37]
	v_mfma_f32_16x16x32_bf16 v[26:29], v[196:199], v[212:215], v[26:29]
	v_mfma_f32_16x16x32_bf16 v[18:21], v[180:183], v[220:223], v[18:21]
	v_mfma_f32_16x16x32_bf16 v[10:13], v[196:199], v[220:223], v[10:13]
	v_mfma_f32_16x16x32_bf16 v[6:9], v[180:183], v[228:231], v[6:9]
	v_mfma_f32_16x16x32_bf16 v[2:5], v[196:199], v[228:231], v[2:5]
	v_mfma_f32_16x16x32_bf16 v[50:53], v[192:195], v[208:211], v[50:53]
	v_mfma_f32_16x16x32_bf16 v[42:45], v[200:203], v[208:211], v[42:45]
	v_mfma_f32_16x16x32_bf16 v[34:37], v[192:195], v[216:219], v[34:37]
	v_mfma_f32_16x16x32_bf16 v[26:29], v[200:203], v[216:219], v[26:29]
	v_mfma_f32_16x16x32_bf16 v[18:21], v[192:195], v[224:227], v[18:21]
	v_mfma_f32_16x16x32_bf16 v[10:13], v[200:203], v[224:227], v[10:13]
	v_mfma_f32_16x16x32_bf16 v[6:9], v[192:195], v[232:235], v[6:9]
	v_mfma_f32_16x16x32_bf16 v[2:5], v[200:203], v[232:235], v[2:5]
	s_setprio 0
	s_barrier
	s_add_i32 s33, 0, 0x18000
	s_add_i32 s47, 0, 0x1c000
	v_add_u32_e32 v176, s33, v133
	v_add_u32_e32 v191, s47, v133
	ds_read_b128 v[156:159], v176
	ds_read_b128 v[168:171], v176 offset:1024
	ds_read_b128 v[172:175], v176 offset:2048
	ds_read_b128 v[176:179], v176 offset:3072
	ds_read_b128 v[180:183], v191
	ds_read_b128 v[192:195], v191 offset:1024
	ds_read_b128 v[196:199], v191 offset:2048
	ds_read_b128 v[200:203], v191 offset:3072
	s_add_u32 s26, s26, 0x40000
	s_addc_u32 s27, s27, 0
	s_mov_b32 m0, s31
	v_lshl_add_u64 v[240:241], s[26:27], 0, v[134:135]
	ds_read_b128 v[204:207], v155 offset:32768
	ds_read_b128 v[208:211], v155 offset:33792
	ds_read_b128 v[212:215], v155 offset:34816
	ds_read_b128 v[216:219], v155 offset:35840
	ds_read_b128 v[220:223], v155 offset:36864
	ds_read_b128 v[224:227], v155 offset:37888
	ds_read_b128 v[228:231], v155 offset:38912
	ds_read_b128 v[232:235], v155 offset:39936
	global_load_lds_dwordx4 v[240:241], off
	v_lshl_add_u64 v[240:241], s[26:27], 0, v[138:139]
	s_mov_b32 m0, s34
	s_nop 0
	global_load_lds_dwordx4 v[240:241], off
	s_waitcnt vmcnt(8)
	s_waitcnt lgkmcnt(0)
	s_barrier
	s_setprio 1
	s_waitcnt lgkmcnt(0)
	v_mfma_f32_16x16x32_bf16 v[126:129], v[156:159], v[204:207], v[126:129]
	v_mfma_f32_16x16x32_bf16 v[122:125], v[172:175], v[204:207], v[122:125]
	v_mfma_f32_16x16x32_bf16 v[118:121], v[156:159], v[212:215], v[118:121]
	v_mfma_f32_16x16x32_bf16 v[110:113], v[172:175], v[212:215], v[110:113]
	v_mfma_f32_16x16x32_bf16 v[102:105], v[156:159], v[220:223], v[102:105]
	v_mfma_f32_16x16x32_bf16 v[94:97], v[172:175], v[220:223], v[94:97]
	v_mfma_f32_16x16x32_bf16 v[82:85], v[156:159], v[228:231], v[82:85]
	v_mfma_f32_16x16x32_bf16 v[74:77], v[172:175], v[228:231], v[74:77]
	v_mfma_f32_16x16x32_bf16 v[126:129], v[168:171], v[208:211], v[126:129]
	v_mfma_f32_16x16x32_bf16 v[122:125], v[176:179], v[208:211], v[122:125]
	v_mfma_f32_16x16x32_bf16 v[118:121], v[168:171], v[216:219], v[118:121]
	v_mfma_f32_16x16x32_bf16 v[110:113], v[176:179], v[216:219], v[110:113]
	v_mfma_f32_16x16x32_bf16 v[102:105], v[168:171], v[224:227], v[102:105]
	v_mfma_f32_16x16x32_bf16 v[94:97], v[176:179], v[224:227], v[94:97]
	v_mfma_f32_16x16x32_bf16 v[82:85], v[168:171], v[232:235], v[82:85]
	v_mfma_f32_16x16x32_bf16 v[74:77], v[176:179], v[232:235], v[74:77]
	v_mfma_f32_16x16x32_bf16 v[114:117], v[180:183], v[204:207], v[114:117]
	v_mfma_f32_16x16x32_bf16 v[106:109], v[196:199], v[204:207], v[106:109]
	v_mfma_f32_16x16x32_bf16 v[98:101], v[180:183], v[212:215], v[98:101]
	v_mfma_f32_16x16x32_bf16 v[90:93], v[196:199], v[212:215], v[90:93]
	v_mfma_f32_16x16x32_bf16 v[86:89], v[180:183], v[220:223], v[86:89]
	v_mfma_f32_16x16x32_bf16 v[78:81], v[196:199], v[220:223], v[78:81]
	v_mfma_f32_16x16x32_bf16 v[70:73], v[180:183], v[228:231], v[70:73]
	v_mfma_f32_16x16x32_bf16 v[66:69], v[196:199], v[228:231], v[66:69]
	v_mfma_f32_16x16x32_bf16 v[114:117], v[192:195], v[208:211], v[114:117]
	v_mfma_f32_16x16x32_bf16 v[106:109], v[200:203], v[208:211], v[106:109]
	v_mfma_f32_16x16x32_bf16 v[98:101], v[192:195], v[216:219], v[98:101]
	v_mfma_f32_16x16x32_bf16 v[90:93], v[200:203], v[216:219], v[90:93]
	v_mfma_f32_16x16x32_bf16 v[86:89], v[192:195], v[224:227], v[86:89]
	v_mfma_f32_16x16x32_bf16 v[78:81], v[200:203], v[224:227], v[78:81]
	v_mfma_f32_16x16x32_bf16 v[70:73], v[192:195], v[232:235], v[70:73]
	v_mfma_f32_16x16x32_bf16 v[66:69], v[200:203], v[232:235], v[66:69]
	s_setprio 0
	s_barrier
; #define PG8_STAGE(bufoff, gbase, voff) do { _Pragma("unroll") for (int _i = 0; _i < 2; ++_i) \
;         __builtin_amdgcn_global_load_lds((const unsigned*)((const char*)(gbase) + (voff)[_i]), (PG8_LAS unsigned*)(lds + (bufoff) + ldsw + _i * 8192), 16, 0, 0); } while (0)
; #define PG8_LDA(dst, b, h) do { _Pragma("unroll") for (int m = 0; m < 4; ++m) _Pragma("unroll") for (int k = 0; k < 2; ++k) dst[m][k] = *(const PG8_LAS bf16x8*)(lds + PG8_SA(b, h) + aoff + m * 2048 + k * 1024); } while (0)
; #define PG8_MMA(ai, bj, At, Bt) do { __builtin_amdgcn_s_setprio(1); _Pragma("unroll") for (int m = 0; m < 4; ++m) _Pragma("unroll") for (int n = 0; n < 2; ++n) _Pragma("unroll") for (int k = 0; k < 2; ++k) \
;         acc[ai][bj][m][n] = __builtin_amdgcn_mfma_f32_16x16x32_bf16(Bt[n][k], At[m][k], acc[ai][bj][m][n], 0, 0, 0); __builtin_amdgcn_s_setprio(0); } while (0)
; #define PG8_WAIT_V(n) asm volatile("s_waitcnt vmcnt(" #n ")" ::: "memory")
; #define PG8_WAIT_L(n) asm volatile("s_waitcnt lgkmcnt(" #n ")" ::: "memory")
; #define PG8_BAR __builtin_amdgcn_s_barrier()
; #define PG8_SCHED __builtin_amdgcn_sched_barrier(0)
; template <class Epi, class Sched, bool ALIGN_EPI = false, bool SP2 = false>
; __device__ __forceinline__ void gemm_phase(PG8_LAS unsigned char* lds, const Gemm g, const Sched& S, const Epi& E) {
;     ...
;         for (int t = 0; t < nt; t += 2) {
;             const bool last = (t == nt - 2);
;             const char* a1 = cA + (size_t)(t + 1) * kstep;
;             const char* a2 = last ? nA : cA + (size_t)(t + 2) * kstep; const char* b2 = last ? nB : cB + (size_t)(t + 2) * kstep;
;     ...
;             PG8_LDA(At, 1, 1); PG8_STAGE(PG8_SB(1, 0), b3, voffB); PG8_STAGE(PG8_SB(1, 1), b3 + hstep, voffB); PG8_STAGE(PG8_SA(1, 0), a3, voffA);
;             PG8_WAIT_V(8); PG8_WAIT_L(0); PG8_BAR; PG8_MMA(1, 0, At, B0); PG8_MMA(1, 1, At, B1); PG8_BAR; PG8_SCHED;
	s_add_i32 s26, s33, s29
	v_lshl_add_u64 v[150:151], v[150:151], 0, s[6:7]
	s_mov_b32 m0, s26
	ds_read_b128 v[204:207], v155 offset:49152
	ds_read_b128 v[208:211], v155 offset:50176
	ds_read_b128 v[212:215], v155 offset:51200
	ds_read_b128 v[216:219], v155 offset:52224
	ds_read_b128 v[220:223], v155 offset:53248
	ds_read_b128 v[224:227], v155 offset:54272
	ds_read_b128 v[228:231], v155 offset:55296
	ds_read_b128 v[232:235], v155 offset:56320
	global_load_lds_dwordx4 v[150:151], off
	s_add_i32 m0, s26, 0x2000
	s_add_u32 s24, s24, 0x40080
	v_lshl_add_u64 v[150:151], v[160:161], 0, s[6:7]
	s_addc_u32 s25, s25, 0
	s_add_i32 s26, s47, s29
	global_load_lds_dwordx4 v[150:151], off
	v_lshl_add_u64 v[150:151], s[24:25], 0, v[136:137]
	s_mov_b32 m0, s26
	s_nop 0
	global_load_lds_dwordx4 v[150:151], off
	v_lshl_add_u64 v[150:151], s[24:25], 0, v[140:141]
	s_add_i32 m0, s26, 0x2000
	s_nop 0
	global_load_lds_dwordx4 v[150:151], off
	v_lshl_add_u64 v[150:151], v[184:185], 0, s[6:7]
	s_mov_b32 m0, s2
	s_nop 0
	global_load_lds_dwordx4 v[150:151], off
	v_lshl_add_u64 v[150:151], v[238:239], 0, s[6:7]
	s_mov_b32 m0, s3
	s_nop 0
	global_load_lds_dwordx4 v[150:151], off
	s_waitcnt vmcnt(8)
	s_waitcnt lgkmcnt(0)
	s_barrier
	s_setprio 1
	s_waitcnt lgkmcnt(0)
	v_mfma_f32_16x16x32_bf16 v[62:65], v[156:159], v[204:207], v[62:65]
	v_mfma_f32_16x16x32_bf16 v[58:61], v[172:175], v[204:207], v[58:61]
	v_mfma_f32_16x16x32_bf16 v[54:57], v[156:159], v[212:215], v[54:57]
	v_mfma_f32_16x16x32_bf16 v[46:49], v[172:175], v[212:215], v[46:49]
	v_mfma_f32_16x16x32_bf16 v[38:41], v[156:159], v[220:223], v[38:41]
	v_mfma_f32_16x16x32_bf16 v[30:33], v[172:175], v[220:223], v[30:33]
	v_mfma_f32_16x16x32_bf16 v[22:25], v[156:159], v[228:231], v[22:25]
	v_mfma_f32_16x16x32_bf16 v[14:17], v[172:175], v[228:231], v[14:17]
	v_mfma_f32_16x16x32_bf16 v[62:65], v[168:171], v[208:211], v[62:65]
	v_mfma_f32_16x16x32_bf16 v[58:61], v[176:179], v[208:211], v[58:61]
	v_mfma_f32_16x16x32_bf16 v[54:57], v[168:171], v[216:219], v[54:57]
	v_mfma_f32_16x16x32_bf16 v[46:49], v[176:179], v[216:219], v[46:49]
	v_mfma_f32_16x16x32_bf16 v[38:41], v[168:171], v[224:227], v[38:41]
	v_mfma_f32_16x16x32_bf16 v[30:33], v[176:179], v[224:227], v[30:33]
	v_mfma_f32_16x16x32_bf16 v[22:25], v[168:171], v[232:235], v[22:25]
	v_mfma_f32_16x16x32_bf16 v[14:17], v[176:179], v[232:235], v[14:17]
	v_mfma_f32_16x16x32_bf16 v[50:53], v[180:183], v[204:207], v[50:53]
	v_mfma_f32_16x16x32_bf16 v[42:45], v[196:199], v[204:207], v[42:45]
	v_mfma_f32_16x16x32_bf16 v[34:37], v[180:183], v[212:215], v[34:37]
	v_mfma_f32_16x16x32_bf16 v[26:29], v[196:199], v[212:215], v[26:29]
	v_mfma_f32_16x16x32_bf16 v[18:21], v[180:183], v[220:223], v[18:21]
	v_mfma_f32_16x16x32_bf16 v[10:13], v[196:199], v[220:223], v[10:13]
	v_mfma_f32_16x16x32_bf16 v[6:9], v[180:183], v[228:231], v[6:9]
	v_mfma_f32_16x16x32_bf16 v[2:5], v[196:199], v[228:231], v[2:5]
	v_mfma_f32_16x16x32_bf16 v[50:53], v[192:195], v[208:211], v[50:53]
	v_mfma_f32_16x16x32_bf16 v[42:45], v[200:203], v[208:211], v[42:45]
	v_mfma_f32_16x16x32_bf16 v[34:37], v[192:195], v[216:219], v[34:37]
	v_mfma_f32_16x16x32_bf16 v[26:29], v[200:203], v[216:219], v[26:29]
	v_mfma_f32_16x16x32_bf16 v[18:21], v[192:195], v[224:227], v[18:21]
	v_mfma_f32_16x16x32_bf16 v[10:13], v[200:203], v[224:227], v[10:13]
	v_mfma_f32_16x16x32_bf16 v[6:9], v[192:195], v[232:235], v[6:9]
	v_mfma_f32_16x16x32_bf16 v[2:5], v[200:203], v[232:235], v[2:5]
	s_setprio 0
	s_barrier
	s_add_i32 s46, s46, 2
	s_add_u32 s22, s22, 0x100
	s_addc_u32 s23, s23, 0
	s_add_u32 s44, s44, 0x100
	s_addc_u32 s45, s45, 0
	s_cmp_gt_u32 s46, 13
	s_cbranch_scc0 .LBB0_1423
	s_and_b64 vcc, exec, s[8:9]
	s_cbranch_vccz .LBB0_1426
	s_barrier

; #define PG8_STAGE(bufoff, gbase, voff) do { _Pragma("unroll") for (int _i = 0; _i < 2; ++_i) \
;         __builtin_amdgcn_global_load_lds((const unsigned*)((const char*)(gbase) + (voff)[_i]), (PG8_LAS unsigned*)(lds + (bufoff) + ldsw + _i * 8192), 16, 0, 0); } while (0)
; #define PG8_LDA(dst, b, h) do { _Pragma("unroll") for (int m = 0; m < 4; ++m) _Pragma("unroll") for (int k = 0; k < 2; ++k) dst[m][k] = *(const PG8_LAS bf16x8*)(lds + PG8_SA(b, h) + aoff + m * 2048 + k * 1024); } while (0)
; #define PG8_LDB(dst, b, h) do { _Pragma("unroll") for (int n = 0; n < 2; ++n) _Pragma("unroll") for (int k = 0; k < 2; ++k) dst[n][k] = *(const PG8_LAS bf16x8*)(lds + PG8_SB(b, h) + boff + n * 2048 + k * 1024); } while (0)
; #define PG8_MMA(ai, bj, At, Bt) do { __builtin_amdgcn_s_setprio(1); _Pragma("unroll") for (int m = 0; m < 4; ++m) _Pragma("unroll") for (int n = 0; n < 2; ++n) _Pragma("unroll") for (int k = 0; k < 2; ++k) \
;         acc[ai][bj][m][n] = __builtin_amdgcn_mfma_f32_16x16x32_bf16(Bt[n][k], At[m][k], acc[ai][bj][m][n], 0, 0, 0); __builtin_amdgcn_s_setprio(0); } while (0)
; #define PG8_WAIT_V(n) asm volatile("s_waitcnt vmcnt(" #n ")" ::: "memory")
; #define PG8_WAIT_L(n) asm volatile("s_waitcnt lgkmcnt(" #n ")" ::: "memory")
; #define PG8_BAR __builtin_amdgcn_s_barrier()
; #define PG8_SCHED __builtin_amdgcn_sched_barrier(0)
; template <class Epi, class Sched, bool ALIGN_EPI = false, bool SP2 = false>
; __device__ __forceinline__ void gemm_phase(PG8_LAS unsigned char* lds, const Gemm g, const Sched& S, const Epi& E) {
;     ...
;             PG8_LDB(B0, 0, 0); PG8_LDB(B1, 0, 1); PG8_SCHED; PG8_LDA(At, 0, 0); PG8_STAGE(PG8_SA(1, 1), a1 + hstep, voffA);
;             PG8_WAIT_V(8); PG8_WAIT_L(0); PG8_BAR; PG8_MMA(0, 0, At, B0); PG8_MMA(0, 1, At, B1); PG8_BAR; PG8_SCHED;
;             PG8_LDA(At, 0, 1); PG8_STAGE(PG8_SB(0, 0), b2, voffB); PG8_STAGE(PG8_SB(0, 1), b2 + hstep, voffB); PG8_STAGE(PG8_SA(0, 0), a2, voffA);
;             PG8_WAIT_V(8); PG8_WAIT_L(0); PG8_BAR; PG8_MMA(1, 0, At, B0); PG8_MMA(1, 1, At, B1); PG8_BAR; PG8_SCHED;
.LBB0_1563:
	ds_read_b128 v[156:159], v152
	ds_read_b128 v[168:171], v152 offset:1024
	ds_read_b128 v[172:175], v152 offset:2048
	ds_read_b128 v[176:179], v152 offset:3072
	ds_read_b128 v[180:183], v153
	ds_read_b128 v[192:195], v153 offset:1024
	ds_read_b128 v[196:199], v153 offset:2048
	ds_read_b128 v[200:203], v153 offset:3072
	s_add_u32 s22, s20, 0xfffc0080
	s_addc_u32 s23, s21, -1
	s_cmp_eq_u32 s45, 12
	s_cselect_b32 s25, s13, s23
	s_cselect_b32 s24, s41, s22
	s_cselect_b32 s23, s11, s44
	s_cselect_b32 s22, s42, s43
	v_lshl_add_u64 v[148:149], s[20:21], 0, v[140:141]
	s_add_i32 m0, s19, 0xc000
	ds_read_b128 v[204:207], v154
	ds_read_b128 v[208:211], v154 offset:1024
	ds_read_b128 v[212:215], v154 offset:2048
	ds_read_b128 v[216:219], v154 offset:3072
	ds_read_b128 v[220:223], v154 offset:4096
	ds_read_b128 v[224:227], v154 offset:5120
	ds_read_b128 v[228:231], v154 offset:6144
	ds_read_b128 v[232:235], v154 offset:7168
	global_load_lds_dwordx4 v[148:149], off
	v_lshl_add_u64 v[148:149], s[20:21], 0, v[142:143]
	s_add_i32 m0, s19, 0xe000
	s_nop 0
	global_load_lds_dwordx4 v[148:149], off
	s_waitcnt vmcnt(8)
	s_waitcnt lgkmcnt(0)
	s_barrier
	s_setprio 1
	s_waitcnt lgkmcnt(0)
	v_mfma_f32_16x16x32_bf16 v[118:121], v[156:159], v[204:207], v[118:121]
	v_mfma_f32_16x16x32_bf16 v[114:117], v[172:175], v[204:207], v[114:117]
	v_mfma_f32_16x16x32_bf16 v[110:113], v[156:159], v[212:215], v[110:113]
	v_mfma_f32_16x16x32_bf16 v[106:109], v[172:175], v[212:215], v[106:109]
	v_mfma_f32_16x16x32_bf16 v[94:97], v[156:159], v[220:223], v[94:97]
	v_mfma_f32_16x16x32_bf16 v[90:93], v[172:175], v[220:223], v[90:93]
	v_mfma_f32_16x16x32_bf16 v[78:81], v[156:159], v[228:231], v[78:81]
	v_mfma_f32_16x16x32_bf16 v[74:77], v[172:175], v[228:231], v[74:77]
	v_mfma_f32_16x16x32_bf16 v[118:121], v[168:171], v[208:211], v[118:121]
	v_mfma_f32_16x16x32_bf16 v[114:117], v[176:179], v[208:211], v[114:117]
	v_mfma_f32_16x16x32_bf16 v[110:113], v[168:171], v[216:219], v[110:113]
	v_mfma_f32_16x16x32_bf16 v[106:109], v[176:179], v[216:219], v[106:109]
	v_mfma_f32_16x16x32_bf16 v[94:97], v[168:171], v[224:227], v[94:97]
	v_mfma_f32_16x16x32_bf16 v[90:93], v[176:179], v[224:227], v[90:93]
	v_mfma_f32_16x16x32_bf16 v[78:81], v[168:171], v[232:235], v[78:81]
	v_mfma_f32_16x16x32_bf16 v[74:77], v[176:179], v[232:235], v[74:77]
	v_mfma_f32_16x16x32_bf16 v[126:129], v[180:183], v[204:207], v[126:129]
	v_mfma_f32_16x16x32_bf16 v[122:125], v[196:199], v[204:207], v[122:125]
	v_mfma_f32_16x16x32_bf16 v[102:105], v[180:183], v[212:215], v[102:105]
	v_mfma_f32_16x16x32_bf16 v[98:101], v[196:199], v[212:215], v[98:101]
	v_mfma_f32_16x16x32_bf16 v[86:89], v[180:183], v[220:223], v[86:89]
	v_mfma_f32_16x16x32_bf16 v[82:85], v[196:199], v[220:223], v[82:85]
	v_mfma_f32_16x16x32_bf16 v[70:73], v[180:183], v[228:231], v[70:73]
	v_mfma_f32_16x16x32_bf16 v[66:69], v[196:199], v[228:231], v[66:69]
	v_mfma_f32_16x16x32_bf16 v[126:129], v[192:195], v[208:211], v[126:129]
	v_mfma_f32_16x16x32_bf16 v[122:125], v[200:203], v[208:211], v[122:125]
	v_mfma_f32_16x16x32_bf16 v[102:105], v[192:195], v[216:219], v[102:105]
	v_mfma_f32_16x16x32_bf16 v[98:101], v[200:203], v[216:219], v[98:101]
	v_mfma_f32_16x16x32_bf16 v[86:89], v[192:195], v[224:227], v[86:89]
	v_mfma_f32_16x16x32_bf16 v[82:85], v[200:203], v[224:227], v[82:85]
	v_mfma_f32_16x16x32_bf16 v[70:73], v[192:195], v[232:235], v[70:73]
	v_mfma_f32_16x16x32_bf16 v[66:69], v[200:203], v[232:235], v[66:69]
	s_setprio 0
	s_barrier
	s_add_i32 s33, s37, s27
	v_lshl_add_u64 v[148:149], s[22:23], 0, v[134:135]
	s_mov_b32 m0, s33
	ds_read_b128 v[204:207], v154 offset:16384
	ds_read_b128 v[208:211], v154 offset:17408
	ds_read_b128 v[212:215], v154 offset:18432
	ds_read_b128 v[216:219], v154 offset:19456
	ds_read_b128 v[220:223], v154 offset:20480
	ds_read_b128 v[224:227], v154 offset:21504
	ds_read_b128 v[228:231], v154 offset:22528
	ds_read_b128 v[232:235], v154 offset:23552
	global_load_lds_dwordx4 v[148:149], off
	s_add_i32 m0, s33, 0x2000
	s_add_u32 s46, s22, 0x40000
	v_lshl_add_u64 v[160:161], s[22:23], 0, v[138:139]
	s_addc_u32 s47, s23, 0
	s_add_i32 s33, s38, s27
	global_load_lds_dwordx4 v[160:161], off
	v_lshl_add_u64 v[184:185], s[46:47], 0, v[134:135]
	s_mov_b32 m0, s33
	v_lshl_add_u64 v[238:239], s[24:25], 0, v[136:137]
	global_load_lds_dwordx4 v[184:185], off
	v_lshl_add_u64 v[184:185], s[46:47], 0, v[138:139]
	s_add_i32 m0, s33, 0x2000
	s_nop 0
	global_load_lds_dwordx4 v[184:185], off
	v_lshl_add_u64 v[184:185], s[24:25], 0, v[132:133]
	s_mov_b32 m0, s19
	s_nop 0
	global_load_lds_dwordx4 v[184:185], off
	s_mov_b32 m0, s28
	s_nop 0
	global_load_lds_dwordx4 v[238:239], off
	s_waitcnt vmcnt(8)
	s_waitcnt lgkmcnt(0)
	s_barrier
; #define PG8_STAGE(bufoff, gbase, voff) do { _Pragma("unroll") for (int _i = 0; _i < 2; ++_i) \
;         __builtin_amdgcn_global_load_lds((const unsigned*)((const char*)(gbase) + (voff)[_i]), (PG8_LAS unsigned*)(lds + (bufoff) + ldsw + _i * 8192), 16, 0, 0); } while (0)
; #define PG8_LDA(dst, b, h) do { _Pragma("unroll") for (int m = 0; m < 4; ++m) _Pragma("unroll") for (int k = 0; k < 2; ++k) dst[m][k] = *(const PG8_LAS bf16x8*)(lds + PG8_SA(b, h) + aoff + m * 2048 + k * 1024); } while (0)
; #define PG8_LDB(dst, b, h) do { _Pragma("unroll") for (int n = 0; n < 2; ++n) _Pragma("unroll") for (int k = 0; k < 2; ++k) dst[n][k] = *(const PG8_LAS bf16x8*)(lds + PG8_SB(b, h) + boff + n * 2048 + k * 1024); } while (0)
; #define PG8_MMA(ai, bj, At, Bt) do { __builtin_amdgcn_s_setprio(1); _Pragma("unroll") for (int m = 0; m < 4; ++m) _Pragma("unroll") for (int n = 0; n < 2; ++n) _Pragma("unroll") for (int k = 0; k < 2; ++k) \
;         acc[ai][bj][m][n] = __builtin_amdgcn_mfma_f32_16x16x32_bf16(Bt[n][k], At[m][k], acc[ai][bj][m][n], 0, 0, 0); __builtin_amdgcn_s_setprio(0); } while (0)
; #define PG8_WAIT_V(n) asm volatile("s_waitcnt vmcnt(" #n ")" ::: "memory")
; #define PG8_WAIT_L(n) asm volatile("s_waitcnt lgkmcnt(" #n ")" ::: "memory")
; #define PG8_BAR __builtin_amdgcn_s_barrier()
; #define PG8_SCHED __builtin_amdgcn_sched_barrier(0)
; template <class Epi, class Sched, bool ALIGN_EPI = false, bool SP2 = false>
; __device__ __forceinline__ void gemm_phase(PG8_LAS unsigned char* lds, const Gemm g, const Sched& S, const Epi& E) {
;     ...
;             PG8_WAIT_V(8); PG8_WAIT_L(0); PG8_BAR; PG8_MMA(1, 0, At, B0); PG8_MMA(1, 1, At, B1); PG8_BAR; PG8_SCHED;
;             PG8_LDB(B0, 1, 0); PG8_LDB(B1, 1, 1); PG8_SCHED; PG8_LDA(At, 1, 0); PG8_STAGE(PG8_SA(0, 1), a2 + hstep, voffA);
;             PG8_WAIT_V(8); PG8_WAIT_L(0); PG8_BAR; PG8_MMA(0, 0, At, B0); PG8_MMA(0, 1, At, B1); PG8_BAR; PG8_SCHED;
	s_setprio 1
	s_waitcnt lgkmcnt(0)
	v_mfma_f32_16x16x32_bf16 v[62:65], v[156:159], v[204:207], v[62:65]
	v_mfma_f32_16x16x32_bf16 v[58:61], v[172:175], v[204:207], v[58:61]
	v_mfma_f32_16x16x32_bf16 v[46:49], v[156:159], v[212:215], v[46:49]
	v_mfma_f32_16x16x32_bf16 v[42:45], v[172:175], v[212:215], v[42:45]
	v_mfma_f32_16x16x32_bf16 v[30:33], v[156:159], v[220:223], v[30:33]
	v_mfma_f32_16x16x32_bf16 v[26:29], v[172:175], v[220:223], v[26:29]
	v_mfma_f32_16x16x32_bf16 v[14:17], v[156:159], v[228:231], v[14:17]
	v_mfma_f32_16x16x32_bf16 v[10:13], v[172:175], v[228:231], v[10:13]
	v_mfma_f32_16x16x32_bf16 v[62:65], v[168:171], v[208:211], v[62:65]
	v_mfma_f32_16x16x32_bf16 v[58:61], v[176:179], v[208:211], v[58:61]
	v_mfma_f32_16x16x32_bf16 v[46:49], v[168:171], v[216:219], v[46:49]
	v_mfma_f32_16x16x32_bf16 v[42:45], v[176:179], v[216:219], v[42:45]
	v_mfma_f32_16x16x32_bf16 v[30:33], v[168:171], v[224:227], v[30:33]
	v_mfma_f32_16x16x32_bf16 v[26:29], v[176:179], v[224:227], v[26:29]
	v_mfma_f32_16x16x32_bf16 v[14:17], v[168:171], v[232:235], v[14:17]
	v_mfma_f32_16x16x32_bf16 v[10:13], v[176:179], v[232:235], v[10:13]
	v_mfma_f32_16x16x32_bf16 v[54:57], v[180:183], v[204:207], v[54:57]
	v_mfma_f32_16x16x32_bf16 v[50:53], v[196:199], v[204:207], v[50:53]
	v_mfma_f32_16x16x32_bf16 v[38:41], v[180:183], v[212:215], v[38:41]
	v_mfma_f32_16x16x32_bf16 v[34:37], v[196:199], v[212:215], v[34:37]
	v_mfma_f32_16x16x32_bf16 v[22:25], v[180:183], v[220:223], v[22:25]
	v_mfma_f32_16x16x32_bf16 v[18:21], v[196:199], v[220:223], v[18:21]
	v_mfma_f32_16x16x32_bf16 v[6:9], v[180:183], v[228:231], v[6:9]
	v_mfma_f32_16x16x32_bf16 v[2:5], v[196:199], v[228:231], v[2:5]
	v_mfma_f32_16x16x32_bf16 v[54:57], v[192:195], v[208:211], v[54:57]
	v_mfma_f32_16x16x32_bf16 v[50:53], v[200:203], v[208:211], v[50:53]
	v_mfma_f32_16x16x32_bf16 v[38:41], v[192:195], v[216:219], v[38:41]
	v_mfma_f32_16x16x32_bf16 v[34:37], v[200:203], v[216:219], v[34:37]
	v_mfma_f32_16x16x32_bf16 v[22:25], v[192:195], v[224:227], v[22:25]
	v_mfma_f32_16x16x32_bf16 v[18:21], v[200:203], v[224:227], v[18:21]
	v_mfma_f32_16x16x32_bf16 v[6:9], v[192:195], v[232:235], v[6:9]
	v_mfma_f32_16x16x32_bf16 v[2:5], v[200:203], v[232:235], v[2:5]
	s_setprio 0
	s_barrier
	s_add_i32 s33, 0, 0x18000
	v_add_u32_e32 v155, s33, v150
	s_add_i32 s46, 0, 0x1c000
	ds_read_b128 v[156:159], v155
	ds_read_b128 v[168:171], v155 offset:1024
	ds_read_b128 v[172:175], v155 offset:2048
	ds_read_b128 v[176:179], v155 offset:3072
	v_add_u32_e32 v155, s46, v150
	ds_read_b128 v[180:183], v155
	ds_read_b128 v[192:195], v155 offset:1024
	ds_read_b128 v[196:199], v155 offset:2048
	ds_read_b128 v[200:203], v155 offset:3072
	s_add_u32 s24, s24, 0x40000
	s_addc_u32 s25, s25, 0
	s_mov_b32 m0, s29
	v_lshl_add_u64 v[240:241], s[24:25], 0, v[132:133]
	ds_read_b128 v[204:207], v154 offset:32768
	ds_read_b128 v[208:211], v154 offset:33792
	ds_read_b128 v[212:215], v154 offset:34816
	ds_read_b128 v[216:219], v154 offset:35840
	ds_read_b128 v[220:223], v154 offset:36864
	ds_read_b128 v[224:227], v154 offset:37888
	ds_read_b128 v[228:231], v154 offset:38912
	ds_read_b128 v[232:235], v154 offset:39936
	global_load_lds_dwordx4 v[240:241], off
	v_lshl_add_u64 v[240:241], s[24:25], 0, v[136:137]
	s_mov_b32 m0, s30
	s_nop 0
	global_load_lds_dwordx4 v[240:241], off
	s_waitcnt vmcnt(8)
	s_waitcnt lgkmcnt(0)
	s_barrier
	s_setprio 1
	s_waitcnt lgkmcnt(0)
	v_mfma_f32_16x16x32_bf16 v[118:121], v[156:159], v[204:207], v[118:121]
	v_mfma_f32_16x16x32_bf16 v[114:117], v[172:175], v[204:207], v[114:117]
	v_mfma_f32_16x16x32_bf16 v[110:113], v[156:159], v[212:215], v[110:113]
	v_mfma_f32_16x16x32_bf16 v[106:109], v[172:175], v[212:215], v[106:109]
	v_mfma_f32_16x16x32_bf16 v[94:97], v[156:159], v[220:223], v[94:97]
	v_mfma_f32_16x16x32_bf16 v[90:93], v[172:175], v[220:223], v[90:93]
	v_mfma_f32_16x16x32_bf16 v[78:81], v[156:159], v[228:231], v[78:81]
	v_mfma_f32_16x16x32_bf16 v[74:77], v[172:175], v[228:231], v[74:77]
	v_mfma_f32_16x16x32_bf16 v[118:121], v[168:171], v[208:211], v[118:121]
	v_mfma_f32_16x16x32_bf16 v[114:117], v[176:179], v[208:211], v[114:117]
	v_mfma_f32_16x16x32_bf16 v[110:113], v[168:171], v[216:219], v[110:113]
	v_mfma_f32_16x16x32_bf16 v[106:109], v[176:179], v[216:219], v[106:109]
	v_mfma_f32_16x16x32_bf16 v[94:97], v[168:171], v[224:227], v[94:97]
	v_mfma_f32_16x16x32_bf16 v[90:93], v[176:179], v[224:227], v[90:93]
	v_mfma_f32_16x16x32_bf16 v[78:81], v[168:171], v[232:235], v[78:81]
	v_mfma_f32_16x16x32_bf16 v[74:77], v[176:179], v[232:235], v[74:77]
	v_mfma_f32_16x16x32_bf16 v[126:129], v[180:183], v[204:207], v[126:129]
	v_mfma_f32_16x16x32_bf16 v[122:125], v[196:199], v[204:207], v[122:125]
	v_mfma_f32_16x16x32_bf16 v[102:105], v[180:183], v[212:215], v[102:105]
	v_mfma_f32_16x16x32_bf16 v[98:101], v[196:199], v[212:215], v[98:101]
	v_mfma_f32_16x16x32_bf16 v[86:89], v[180:183], v[220:223], v[86:89]
	v_mfma_f32_16x16x32_bf16 v[82:85], v[196:199], v[220:223], v[82:85]
	v_mfma_f32_16x16x32_bf16 v[70:73], v[180:183], v[228:231], v[70:73]
	v_mfma_f32_16x16x32_bf16 v[66:69], v[196:199], v[228:231], v[66:69]
	v_mfma_f32_16x16x32_bf16 v[126:129], v[192:195], v[208:211], v[126:129]
	v_mfma_f32_16x16x32_bf16 v[122:125], v[200:203], v[208:211], v[122:125]
	v_mfma_f32_16x16x32_bf16 v[102:105], v[192:195], v[216:219], v[102:105]
	v_mfma_f32_16x16x32_bf16 v[98:101], v[200:203], v[216:219], v[98:101]
	v_mfma_f32_16x16x32_bf16 v[86:89], v[192:195], v[224:227], v[86:89]
	v_mfma_f32_16x16x32_bf16 v[82:85], v[200:203], v[224:227], v[82:85]
	v_mfma_f32_16x16x32_bf16 v[70:73], v[192:195], v[232:235], v[70:73]
	v_mfma_f32_16x16x32_bf16 v[66:69], v[200:203], v[232:235], v[66:69]
	s_setprio 0
	s_barrier
; #define PG8_STAGE(bufoff, gbase, voff) do { _Pragma("unroll") for (int _i = 0; _i < 2; ++_i) \
;         __builtin_amdgcn_global_load_lds((const unsigned*)((const char*)(gbase) + (voff)[_i]), (PG8_LAS unsigned*)(lds + (bufoff) + ldsw + _i * 8192), 16, 0, 0); } while (0)
; #define PG8_LDA(dst, b, h) do { _Pragma("unroll") for (int m = 0; m < 4; ++m) _Pragma("unroll") for (int k = 0; k < 2; ++k) dst[m][k] = *(const PG8_LAS bf16x8*)(lds + PG8_SA(b, h) + aoff + m * 2048 + k * 1024); } while (0)
; #define PG8_MMA(ai, bj, At, Bt) do { __builtin_amdgcn_s_setprio(1); _Pragma("unroll") for (int m = 0; m < 4; ++m) _Pragma("unroll") for (int n = 0; n < 2; ++n) _Pragma("unroll") for (int k = 0; k < 2; ++k) \
;         acc[ai][bj][m][n] = __builtin_amdgcn_mfma_f32_16x16x32_bf16(Bt[n][k], At[m][k], acc[ai][bj][m][n], 0, 0, 0); __builtin_amdgcn_s_setprio(0); } while (0)
; #define PG8_WAIT_V(n) asm volatile("s_waitcnt vmcnt(" #n ")" ::: "memory")
; #define PG8_WAIT_L(n) asm volatile("s_waitcnt lgkmcnt(" #n ")" ::: "memory")
; #define PG8_BAR __builtin_amdgcn_s_barrier()
; #define PG8_SCHED __builtin_amdgcn_sched_barrier(0)
; template <class Epi, class Sched, bool ALIGN_EPI = false, bool SP2 = false>
; __device__ __forceinline__ void gemm_phase(PG8_LAS unsigned char* lds, const Gemm g, const Sched& S, const Epi& E) {
;     ...
;         for (int t = 0; t < nt; t += 2) {
;             const bool last = (t == nt - 2);
;             const char* a1 = cA + (size_t)(t + 1) * kstep;
;             const char* a2 = last ? nA : cA + (size_t)(t + 2) * kstep; const char* b2 = last ? nB : cB + (size_t)(t + 2) * kstep;
;     ...
;             PG8_LDA(At, 1, 1); PG8_STAGE(PG8_SB(1, 0), b3, voffB); PG8_STAGE(PG8_SB(1, 1), b3 + hstep, voffB); PG8_STAGE(PG8_SA(1, 0), a3, voffA);
;             PG8_WAIT_V(8); PG8_WAIT_L(0); PG8_BAR; PG8_MMA(1, 0, At, B0); PG8_MMA(1, 1, At, B1); PG8_BAR; PG8_SCHED;
	s_add_i32 s24, s33, s27
	v_lshl_add_u64 v[148:149], v[148:149], 0, s[2:3]
	s_mov_b32 m0, s24
	ds_read_b128 v[204:207], v154 offset:49152
	ds_read_b128 v[208:211], v154 offset:50176
	ds_read_b128 v[212:215], v154 offset:51200
	ds_read_b128 v[216:219], v154 offset:52224
	ds_read_b128 v[220:223], v154 offset:53248
	ds_read_b128 v[224:227], v154 offset:54272
	ds_read_b128 v[228:231], v154 offset:55296
	ds_read_b128 v[232:235], v154 offset:56320
	global_load_lds_dwordx4 v[148:149], off
	s_add_i32 m0, s24, 0x2000
	s_add_u32 s22, s22, 0x40080
	v_lshl_add_u64 v[148:149], v[160:161], 0, s[2:3]
	s_addc_u32 s23, s23, 0
	s_add_i32 s24, s46, s27
	global_load_lds_dwordx4 v[148:149], off
	v_lshl_add_u64 v[148:149], s[22:23], 0, v[134:135]
	s_mov_b32 m0, s24
	s_nop 0
	global_load_lds_dwordx4 v[148:149], off
	v_lshl_add_u64 v[148:149], s[22:23], 0, v[138:139]
	s_add_i32 m0, s24, 0x2000
	s_nop 0
	global_load_lds_dwordx4 v[148:149], off
	v_lshl_add_u64 v[148:149], v[184:185], 0, s[2:3]
	s_mov_b32 m0, s34
	s_nop 0
	global_load_lds_dwordx4 v[148:149], off
	v_lshl_add_u64 v[148:149], v[238:239], 0, s[2:3]
	s_mov_b32 m0, s35
	s_nop 0
	global_load_lds_dwordx4 v[148:149], off
	s_waitcnt vmcnt(8)
	s_waitcnt lgkmcnt(0)
	s_barrier
	s_setprio 1
	s_waitcnt lgkmcnt(0)
	v_mfma_f32_16x16x32_bf16 v[62:65], v[156:159], v[204:207], v[62:65]
	v_mfma_f32_16x16x32_bf16 v[58:61], v[172:175], v[204:207], v[58:61]
	v_mfma_f32_16x16x32_bf16 v[46:49], v[156:159], v[212:215], v[46:49]
	v_mfma_f32_16x16x32_bf16 v[42:45], v[172:175], v[212:215], v[42:45]
	v_mfma_f32_16x16x32_bf16 v[30:33], v[156:159], v[220:223], v[30:33]
	v_mfma_f32_16x16x32_bf16 v[26:29], v[172:175], v[220:223], v[26:29]
	v_mfma_f32_16x16x32_bf16 v[14:17], v[156:159], v[228:231], v[14:17]
	v_mfma_f32_16x16x32_bf16 v[10:13], v[172:175], v[228:231], v[10:13]
	v_mfma_f32_16x16x32_bf16 v[62:65], v[168:171], v[208:211], v[62:65]
	v_mfma_f32_16x16x32_bf16 v[58:61], v[176:179], v[208:211], v[58:61]
	v_mfma_f32_16x16x32_bf16 v[46:49], v[168:171], v[216:219], v[46:49]
	v_mfma_f32_16x16x32_bf16 v[42:45], v[176:179], v[216:219], v[42:45]
	v_mfma_f32_16x16x32_bf16 v[30:33], v[168:171], v[224:227], v[30:33]
	v_mfma_f32_16x16x32_bf16 v[26:29], v[176:179], v[224:227], v[26:29]
	v_mfma_f32_16x16x32_bf16 v[14:17], v[168:171], v[232:235], v[14:17]
	v_mfma_f32_16x16x32_bf16 v[10:13], v[176:179], v[232:235], v[10:13]
	v_mfma_f32_16x16x32_bf16 v[54:57], v[180:183], v[204:207], v[54:57]
	v_mfma_f32_16x16x32_bf16 v[50:53], v[196:199], v[204:207], v[50:53]
	v_mfma_f32_16x16x32_bf16 v[38:41], v[180:183], v[212:215], v[38:41]
	v_mfma_f32_16x16x32_bf16 v[34:37], v[196:199], v[212:215], v[34:37]
	v_mfma_f32_16x16x32_bf16 v[22:25], v[180:183], v[220:223], v[22:25]
	v_mfma_f32_16x16x32_bf16 v[18:21], v[196:199], v[220:223], v[18:21]
	v_mfma_f32_16x16x32_bf16 v[6:9], v[180:183], v[228:231], v[6:9]
	v_mfma_f32_16x16x32_bf16 v[2:5], v[196:199], v[228:231], v[2:5]
	v_mfma_f32_16x16x32_bf16 v[54:57], v[192:195], v[208:211], v[54:57]
	v_mfma_f32_16x16x32_bf16 v[50:53], v[200:203], v[208:211], v[50:53]
	v_mfma_f32_16x16x32_bf16 v[38:41], v[192:195], v[216:219], v[38:41]
	v_mfma_f32_16x16x32_bf16 v[34:37], v[200:203], v[216:219], v[34:37]
	v_mfma_f32_16x16x32_bf16 v[22:25], v[192:195], v[224:227], v[22:25]
	v_mfma_f32_16x16x32_bf16 v[18:21], v[200:203], v[224:227], v[18:21]
	v_mfma_f32_16x16x32_bf16 v[6:9], v[192:195], v[232:235], v[6:9]
	v_mfma_f32_16x16x32_bf16 v[2:5], v[200:203], v[232:235], v[2:5]
	s_setprio 0
	s_barrier
	s_add_i32 s45, s45, 2
	s_add_u32 s20, s20, 0x100
	s_addc_u32 s21, s21, 0
	s_add_u32 s43, s43, 0x100
	s_addc_u32 s44, s44, 0
	s_cmp_gt_u32 s45, 13
	s_cbranch_scc0 .LBB0_1563
	s_and_b64 vcc, exec, s[8:9]
	s_cbranch_vccz .LBB0_1566
	s_barrier

; #define PG8_STAGE(bufoff, gbase, voff) do { _Pragma("unroll") for (int _i = 0; _i < 2; ++_i) \
;         __builtin_amdgcn_global_load_lds((const unsigned*)((const char*)(gbase) + (voff)[_i]), (PG8_LAS unsigned*)(lds + (bufoff) + ldsw + _i * 8192), 16, 0, 0); } while (0)
; #define PG8_LDA(dst, b, h) do { _Pragma("unroll") for (int m = 0; m < 4; ++m) _Pragma("unroll") for (int k = 0; k < 2; ++k) dst[m][k] = *(const PG8_LAS bf16x8*)(lds + PG8_SA(b, h) + aoff + m * 2048 + k * 1024); } while (0)
; #define PG8_LDB(dst, b, h) do { _Pragma("unroll") for (int n = 0; n < 2; ++n) _Pragma("unroll") for (int k = 0; k < 2; ++k) dst[n][k] = *(const PG8_LAS bf16x8*)(lds + PG8_SB(b, h) + boff + n * 2048 + k * 1024); } while (0)
; #define PG8_MMA(ai, bj, At, Bt) do { __builtin_amdgcn_s_setprio(1); _Pragma("unroll") for (int m = 0; m < 4; ++m) _Pragma("unroll") for (int n = 0; n < 2; ++n) _Pragma("unroll") for (int k = 0; k < 2; ++k) \
;         acc[ai][bj][m][n] = __builtin_amdgcn_mfma_f32_16x16x32_bf16(Bt[n][k], At[m][k], acc[ai][bj][m][n], 0, 0, 0); __builtin_amdgcn_s_setprio(0); } while (0)
; #define PG8_WAIT_V(n) asm volatile("s_waitcnt vmcnt(" #n ")" ::: "memory")
; #define PG8_WAIT_L(n) asm volatile("s_waitcnt lgkmcnt(" #n ")" ::: "memory")
; #define PG8_BAR __builtin_amdgcn_s_barrier()
; #define PG8_SCHED __builtin_amdgcn_sched_barrier(0)
; template <class Epi, class Sched, bool ALIGN_EPI = false, bool SP2 = false>
; __device__ __forceinline__ void gemm_phase(PG8_LAS unsigned char* lds, const Gemm g, const Sched& S, const Epi& E) {
;     ...
;             PG8_LDB(B0, 0, 0); PG8_LDB(B1, 0, 1); PG8_SCHED; PG8_LDA(At, 0, 0); PG8_STAGE(PG8_SA(1, 1), a1 + hstep, voffA);
;             PG8_WAIT_V(8); PG8_WAIT_L(0); PG8_BAR; PG8_MMA(0, 0, At, B0); PG8_MMA(0, 1, At, B1); PG8_BAR; PG8_SCHED;
;             PG8_LDA(At, 0, 1); PG8_STAGE(PG8_SB(0, 0), b2, voffB); PG8_STAGE(PG8_SB(0, 1), b2 + hstep, voffB); PG8_STAGE(PG8_SA(0, 0), a2, voffA);
;             PG8_WAIT_V(8); PG8_WAIT_L(0); PG8_BAR; PG8_MMA(1, 0, At, B0); PG8_MMA(1, 1, At, B1); PG8_BAR; PG8_SCHED;
.LBB0_1663:
	ds_read_b128 v[152:155], v149
	ds_read_b128 v[156:159], v149 offset:1024
	ds_read_b128 v[168:171], v149 offset:2048
	ds_read_b128 v[172:175], v149 offset:3072
	ds_read_b128 v[176:179], v150
	ds_read_b128 v[180:183], v150 offset:1024
	ds_read_b128 v[190:193], v150 offset:2048
	ds_read_b128 v[194:197], v150 offset:3072
	s_add_u32 s24, s22, 0x100
	s_addc_u32 s25, s23, 0
	s_cmp_eq_u32 s54, 40
	s_cselect_b32 s29, s1, s25
	s_cselect_b32 s28, s0, s24
	s_cselect_b32 s27, s21, s53
	s_cselect_b32 s26, s20, s52
	v_lshl_add_u64 v[144:145], s[22:23], 0, v[136:137]
	s_add_i32 m0, s34, 0xc000
	ds_read_b128 v[198:201], v151
	ds_read_b128 v[202:205], v151 offset:1024
	ds_read_b128 v[206:209], v151 offset:2048
	ds_read_b128 v[210:213], v151 offset:3072
	ds_read_b128 v[214:217], v151 offset:4096
	ds_read_b128 v[218:221], v151 offset:5120
	ds_read_b128 v[222:225], v151 offset:6144
	ds_read_b128 v[226:229], v151 offset:7168
	global_load_lds_dwordx4 v[144:145], off
	v_lshl_add_u64 v[144:145], s[22:23], 0, v[138:139]
	s_add_i32 m0, s34, 0xe000
	s_nop 0
	global_load_lds_dwordx4 v[144:145], off
	s_waitcnt vmcnt(8)
	s_waitcnt lgkmcnt(0)
	s_barrier
	s_setprio 1
	s_waitcnt lgkmcnt(0)
	v_mfma_f32_16x16x32_bf16 v[124:127], v[152:155], v[198:201], v[124:127]
	v_mfma_f32_16x16x32_bf16 v[120:123], v[168:171], v[198:201], v[120:123]
	v_mfma_f32_16x16x32_bf16 v[116:119], v[152:155], v[206:209], v[116:119]
	v_mfma_f32_16x16x32_bf16 v[108:111], v[168:171], v[206:209], v[108:111]
	v_mfma_f32_16x16x32_bf16 v[100:103], v[152:155], v[214:217], v[100:103]
	v_mfma_f32_16x16x32_bf16 v[92:95], v[168:171], v[214:217], v[92:95]
	v_mfma_f32_16x16x32_bf16 v[84:87], v[152:155], v[222:225], v[84:87]
	v_mfma_f32_16x16x32_bf16 v[76:79], v[168:171], v[222:225], v[76:79]
	v_mfma_f32_16x16x32_bf16 v[124:127], v[156:159], v[202:205], v[124:127]
	v_mfma_f32_16x16x32_bf16 v[120:123], v[172:175], v[202:205], v[120:123]
	v_mfma_f32_16x16x32_bf16 v[116:119], v[156:159], v[210:213], v[116:119]
	v_mfma_f32_16x16x32_bf16 v[108:111], v[172:175], v[210:213], v[108:111]
	v_mfma_f32_16x16x32_bf16 v[100:103], v[156:159], v[218:221], v[100:103]
	v_mfma_f32_16x16x32_bf16 v[92:95], v[172:175], v[218:221], v[92:95]
	v_mfma_f32_16x16x32_bf16 v[84:87], v[156:159], v[226:229], v[84:87]
	v_mfma_f32_16x16x32_bf16 v[76:79], v[172:175], v[226:229], v[76:79]
	v_mfma_f32_16x16x32_bf16 v[112:115], v[176:179], v[198:201], v[112:115]
	v_mfma_f32_16x16x32_bf16 v[104:107], v[190:193], v[198:201], v[104:107]
	v_mfma_f32_16x16x32_bf16 v[96:99], v[176:179], v[206:209], v[96:99]
	v_mfma_f32_16x16x32_bf16 v[88:91], v[190:193], v[206:209], v[88:91]
	v_mfma_f32_16x16x32_bf16 v[80:83], v[176:179], v[214:217], v[80:83]
	v_mfma_f32_16x16x32_bf16 v[72:75], v[190:193], v[214:217], v[72:75]
	v_mfma_f32_16x16x32_bf16 v[68:71], v[176:179], v[222:225], v[68:71]
	v_mfma_f32_16x16x32_bf16 v[64:67], v[190:193], v[222:225], v[64:67]
	v_mfma_f32_16x16x32_bf16 v[112:115], v[180:183], v[202:205], v[112:115]
	v_mfma_f32_16x16x32_bf16 v[104:107], v[194:197], v[202:205], v[104:107]
	v_mfma_f32_16x16x32_bf16 v[96:99], v[180:183], v[210:213], v[96:99]
	v_mfma_f32_16x16x32_bf16 v[88:91], v[194:197], v[210:213], v[88:91]
	v_mfma_f32_16x16x32_bf16 v[80:83], v[180:183], v[218:221], v[80:83]
	v_mfma_f32_16x16x32_bf16 v[72:75], v[194:197], v[218:221], v[72:75]
	v_mfma_f32_16x16x32_bf16 v[68:71], v[180:183], v[226:229], v[68:71]
	v_mfma_f32_16x16x32_bf16 v[64:67], v[194:197], v[226:229], v[64:67]
	s_setprio 0
	s_barrier
	s_add_i32 s22, s42, s31
	v_lshl_add_u64 v[144:145], s[26:27], 0, v[130:131]
	s_mov_b32 m0, s22
	ds_read_b128 v[198:201], v151 offset:16384
	ds_read_b128 v[202:205], v151 offset:17408
	ds_read_b128 v[206:209], v151 offset:18432
	ds_read_b128 v[210:213], v151 offset:19456
	ds_read_b128 v[214:217], v151 offset:20480
	ds_read_b128 v[218:221], v151 offset:21504
	ds_read_b128 v[222:225], v151 offset:22528
	ds_read_b128 v[226:229], v151 offset:23552
	global_load_lds_dwordx4 v[144:145], off
	s_add_i32 m0, s22, 0x2000
	s_add_u32 s22, s26, 0xb0000
	v_lshl_add_u64 v[160:161], s[26:27], 0, v[134:135]
	s_addc_u32 s23, s27, 0
	s_add_i32 s33, s43, s31
	global_load_lds_dwordx4 v[160:161], off
	v_lshl_add_u64 v[184:185], s[22:23], 0, v[130:131]
	s_mov_b32 m0, s33
	v_lshl_add_u64 v[230:231], s[28:29], 0, v[132:133]
	global_load_lds_dwordx4 v[184:185], off
	v_lshl_add_u64 v[184:185], s[22:23], 0, v[134:135]
	s_add_i32 m0, s33, 0x2000
	s_nop 0
	global_load_lds_dwordx4 v[184:185], off
	v_lshl_add_u64 v[184:185], s[28:29], 0, v[128:129]
	s_mov_b32 m0, s34
	s_nop 0
	global_load_lds_dwordx4 v[184:185], off
	s_mov_b32 m0, s35
	s_nop 0
	global_load_lds_dwordx4 v[230:231], off
	s_waitcnt vmcnt(8)
	s_waitcnt lgkmcnt(0)
	s_barrier
; #define PG8_STAGE(bufoff, gbase, voff) do { _Pragma("unroll") for (int _i = 0; _i < 2; ++_i) \
;         __builtin_amdgcn_global_load_lds((const unsigned*)((const char*)(gbase) + (voff)[_i]), (PG8_LAS unsigned*)(lds + (bufoff) + ldsw + _i * 8192), 16, 0, 0); } while (0)
; #define PG8_LDA(dst, b, h) do { _Pragma("unroll") for (int m = 0; m < 4; ++m) _Pragma("unroll") for (int k = 0; k < 2; ++k) dst[m][k] = *(const PG8_LAS bf16x8*)(lds + PG8_SA(b, h) + aoff + m * 2048 + k * 1024); } while (0)
; #define PG8_LDB(dst, b, h) do { _Pragma("unroll") for (int n = 0; n < 2; ++n) _Pragma("unroll") for (int k = 0; k < 2; ++k) dst[n][k] = *(const PG8_LAS bf16x8*)(lds + PG8_SB(b, h) + boff + n * 2048 + k * 1024); } while (0)
; #define PG8_MMA(ai, bj, At, Bt) do { __builtin_amdgcn_s_setprio(1); _Pragma("unroll") for (int m = 0; m < 4; ++m) _Pragma("unroll") for (int n = 0; n < 2; ++n) _Pragma("unroll") for (int k = 0; k < 2; ++k) \
;         acc[ai][bj][m][n] = __builtin_amdgcn_mfma_f32_16x16x32_bf16(Bt[n][k], At[m][k], acc[ai][bj][m][n], 0, 0, 0); __builtin_amdgcn_s_setprio(0); } while (0)
; #define PG8_WAIT_V(n) asm volatile("s_waitcnt vmcnt(" #n ")" ::: "memory")
; #define PG8_WAIT_L(n) asm volatile("s_waitcnt lgkmcnt(" #n ")" ::: "memory")
; #define PG8_BAR __builtin_amdgcn_s_barrier()
; #define PG8_SCHED __builtin_amdgcn_sched_barrier(0)
; template <class Epi, class Sched, bool ALIGN_EPI = false, bool SP2 = false>
; __device__ __forceinline__ void gemm_phase(PG8_LAS unsigned char* lds, const Gemm g, const Sched& S, const Epi& E) {
;     ...
;             PG8_WAIT_V(8); PG8_WAIT_L(0); PG8_BAR; PG8_MMA(1, 0, At, B0); PG8_MMA(1, 1, At, B1); PG8_BAR; PG8_SCHED;
;             PG8_LDB(B0, 1, 0); PG8_LDB(B1, 1, 1); PG8_SCHED; PG8_LDA(At, 1, 0); PG8_STAGE(PG8_SA(0, 1), a2 + hstep, voffA);
;             PG8_WAIT_V(8); PG8_WAIT_L(0); PG8_BAR; PG8_MMA(0, 0, At, B0); PG8_MMA(0, 1, At, B1); PG8_BAR; PG8_SCHED;
	s_setprio 1
	s_waitcnt lgkmcnt(0)
	v_mfma_f32_16x16x32_bf16 v[60:63], v[152:155], v[198:201], v[60:63]
	v_mfma_f32_16x16x32_bf16 v[56:59], v[168:171], v[198:201], v[56:59]
	v_mfma_f32_16x16x32_bf16 v[52:55], v[152:155], v[206:209], v[52:55]
	v_mfma_f32_16x16x32_bf16 v[44:47], v[168:171], v[206:209], v[44:47]
	v_mfma_f32_16x16x32_bf16 v[36:39], v[152:155], v[214:217], v[36:39]
	v_mfma_f32_16x16x32_bf16 v[28:31], v[168:171], v[214:217], v[28:31]
	v_mfma_f32_16x16x32_bf16 v[20:23], v[152:155], v[222:225], v[20:23]
	v_mfma_f32_16x16x32_bf16 v[12:15], v[168:171], v[222:225], v[12:15]
	v_mfma_f32_16x16x32_bf16 v[60:63], v[156:159], v[202:205], v[60:63]
	v_mfma_f32_16x16x32_bf16 v[56:59], v[172:175], v[202:205], v[56:59]
	v_mfma_f32_16x16x32_bf16 v[52:55], v[156:159], v[210:213], v[52:55]
	v_mfma_f32_16x16x32_bf16 v[44:47], v[172:175], v[210:213], v[44:47]
	v_mfma_f32_16x16x32_bf16 v[36:39], v[156:159], v[218:221], v[36:39]
	v_mfma_f32_16x16x32_bf16 v[28:31], v[172:175], v[218:221], v[28:31]
	v_mfma_f32_16x16x32_bf16 v[20:23], v[156:159], v[226:229], v[20:23]
	v_mfma_f32_16x16x32_bf16 v[12:15], v[172:175], v[226:229], v[12:15]
	v_mfma_f32_16x16x32_bf16 v[48:51], v[176:179], v[198:201], v[48:51]
	v_mfma_f32_16x16x32_bf16 v[40:43], v[190:193], v[198:201], v[40:43]
	v_mfma_f32_16x16x32_bf16 v[32:35], v[176:179], v[206:209], v[32:35]
	v_mfma_f32_16x16x32_bf16 v[24:27], v[190:193], v[206:209], v[24:27]
	v_mfma_f32_16x16x32_bf16 v[16:19], v[176:179], v[214:217], v[16:19]
	v_mfma_f32_16x16x32_bf16 v[8:11], v[190:193], v[214:217], v[8:11]
	v_mfma_f32_16x16x32_bf16 v[4:7], v[176:179], v[222:225], v[4:7]
	v_mfma_f32_16x16x32_bf16 v[0:3], v[190:193], v[222:225], v[0:3]
	v_mfma_f32_16x16x32_bf16 v[48:51], v[180:183], v[202:205], v[48:51]
	v_mfma_f32_16x16x32_bf16 v[40:43], v[194:197], v[202:205], v[40:43]
	v_mfma_f32_16x16x32_bf16 v[32:35], v[180:183], v[210:213], v[32:35]
	v_mfma_f32_16x16x32_bf16 v[24:27], v[194:197], v[210:213], v[24:27]
	v_mfma_f32_16x16x32_bf16 v[16:19], v[180:183], v[218:221], v[16:19]
	v_mfma_f32_16x16x32_bf16 v[8:11], v[194:197], v[218:221], v[8:11]
	v_mfma_f32_16x16x32_bf16 v[4:7], v[180:183], v[226:229], v[4:7]
	v_mfma_f32_16x16x32_bf16 v[0:3], v[194:197], v[226:229], v[0:3]
	s_setprio 0
	s_barrier
	s_add_i32 s33, 0, 0x18000
	v_add_u32_e32 v165, s33, v147
	s_add_i32 s55, 0, 0x1c000
	ds_read_b128 v[152:155], v165
	ds_read_b128 v[156:159], v165 offset:1024
	ds_read_b128 v[168:171], v165 offset:2048
	ds_read_b128 v[172:175], v165 offset:3072
	v_add_u32_e32 v165, s55, v147
	ds_read_b128 v[176:179], v165
	ds_read_b128 v[180:183], v165 offset:1024
	ds_read_b128 v[190:193], v165 offset:2048
	ds_read_b128 v[194:197], v165 offset:3072
	s_add_u32 s22, s28, 0xb0000
	s_addc_u32 s23, s29, 0
	s_mov_b32 m0, s36
	v_lshl_add_u64 v[232:233], s[22:23], 0, v[128:129]
	ds_read_b128 v[198:201], v151 offset:32768
	ds_read_b128 v[202:205], v151 offset:33792
	ds_read_b128 v[206:209], v151 offset:34816
	ds_read_b128 v[210:213], v151 offset:35840
	ds_read_b128 v[214:217], v151 offset:36864
	ds_read_b128 v[218:221], v151 offset:37888
	ds_read_b128 v[222:225], v151 offset:38912
	ds_read_b128 v[226:229], v151 offset:39936
	global_load_lds_dwordx4 v[232:233], off
	v_lshl_add_u64 v[232:233], s[22:23], 0, v[132:133]
	s_mov_b32 m0, s37
	s_nop 0
	global_load_lds_dwordx4 v[232:233], off
	s_waitcnt vmcnt(8)
	s_waitcnt lgkmcnt(0)
	s_barrier
	s_setprio 1
	s_waitcnt lgkmcnt(0)
	v_mfma_f32_16x16x32_bf16 v[124:127], v[152:155], v[198:201], v[124:127]
	v_mfma_f32_16x16x32_bf16 v[120:123], v[168:171], v[198:201], v[120:123]
	v_mfma_f32_16x16x32_bf16 v[116:119], v[152:155], v[206:209], v[116:119]
	v_mfma_f32_16x16x32_bf16 v[108:111], v[168:171], v[206:209], v[108:111]
	v_mfma_f32_16x16x32_bf16 v[100:103], v[152:155], v[214:217], v[100:103]
	v_mfma_f32_16x16x32_bf16 v[92:95], v[168:171], v[214:217], v[92:95]
	v_mfma_f32_16x16x32_bf16 v[84:87], v[152:155], v[222:225], v[84:87]
	v_mfma_f32_16x16x32_bf16 v[76:79], v[168:171], v[222:225], v[76:79]
	v_mfma_f32_16x16x32_bf16 v[124:127], v[156:159], v[202:205], v[124:127]
	v_mfma_f32_16x16x32_bf16 v[120:123], v[172:175], v[202:205], v[120:123]
	v_mfma_f32_16x16x32_bf16 v[116:119], v[156:159], v[210:213], v[116:119]
	v_mfma_f32_16x16x32_bf16 v[108:111], v[172:175], v[210:213], v[108:111]
	v_mfma_f32_16x16x32_bf16 v[100:103], v[156:159], v[218:221], v[100:103]
	v_mfma_f32_16x16x32_bf16 v[92:95], v[172:175], v[218:221], v[92:95]
	v_mfma_f32_16x16x32_bf16 v[84:87], v[156:159], v[226:229], v[84:87]
	v_mfma_f32_16x16x32_bf16 v[76:79], v[172:175], v[226:229], v[76:79]
	v_mfma_f32_16x16x32_bf16 v[112:115], v[176:179], v[198:201], v[112:115]
	v_mfma_f32_16x16x32_bf16 v[104:107], v[190:193], v[198:201], v[104:107]
	v_mfma_f32_16x16x32_bf16 v[96:99], v[176:179], v[206:209], v[96:99]
	v_mfma_f32_16x16x32_bf16 v[88:91], v[190:193], v[206:209], v[88:91]
	v_mfma_f32_16x16x32_bf16 v[80:83], v[176:179], v[214:217], v[80:83]
	v_mfma_f32_16x16x32_bf16 v[72:75], v[190:193], v[214:217], v[72:75]
	v_mfma_f32_16x16x32_bf16 v[68:71], v[176:179], v[222:225], v[68:71]
	v_mfma_f32_16x16x32_bf16 v[64:67], v[190:193], v[222:225], v[64:67]
	v_mfma_f32_16x16x32_bf16 v[112:115], v[180:183], v[202:205], v[112:115]
	v_mfma_f32_16x16x32_bf16 v[104:107], v[194:197], v[202:205], v[104:107]
	v_mfma_f32_16x16x32_bf16 v[96:99], v[180:183], v[210:213], v[96:99]
	v_mfma_f32_16x16x32_bf16 v[88:91], v[194:197], v[210:213], v[88:91]
	v_mfma_f32_16x16x32_bf16 v[80:83], v[180:183], v[218:221], v[80:83]
	v_mfma_f32_16x16x32_bf16 v[72:75], v[194:197], v[218:221], v[72:75]
	v_mfma_f32_16x16x32_bf16 v[68:71], v[180:183], v[226:229], v[68:71]
	v_mfma_f32_16x16x32_bf16 v[64:67], v[194:197], v[226:229], v[64:67]
	s_setprio 0
	s_barrier
; #define PG8_STAGE(bufoff, gbase, voff) do { _Pragma("unroll") for (int _i = 0; _i < 2; ++_i) \
;         __builtin_amdgcn_global_load_lds((const unsigned*)((const char*)(gbase) + (voff)[_i]), (PG8_LAS unsigned*)(lds + (bufoff) + ldsw + _i * 8192), 16, 0, 0); } while (0)
; #define PG8_LDA(dst, b, h) do { _Pragma("unroll") for (int m = 0; m < 4; ++m) _Pragma("unroll") for (int k = 0; k < 2; ++k) dst[m][k] = *(const PG8_LAS bf16x8*)(lds + PG8_SA(b, h) + aoff + m * 2048 + k * 1024); } while (0)
; #define PG8_MMA(ai, bj, At, Bt) do { __builtin_amdgcn_s_setprio(1); _Pragma("unroll") for (int m = 0; m < 4; ++m) _Pragma("unroll") for (int n = 0; n < 2; ++n) _Pragma("unroll") for (int k = 0; k < 2; ++k) \
;         acc[ai][bj][m][n] = __builtin_amdgcn_mfma_f32_16x16x32_bf16(Bt[n][k], At[m][k], acc[ai][bj][m][n], 0, 0, 0); __builtin_amdgcn_s_setprio(0); } while (0)
; #define PG8_WAIT_V(n) asm volatile("s_waitcnt vmcnt(" #n ")" ::: "memory")
; #define PG8_WAIT_L(n) asm volatile("s_waitcnt lgkmcnt(" #n ")" ::: "memory")
; #define PG8_BAR __builtin_amdgcn_s_barrier()
; #define PG8_SCHED __builtin_amdgcn_sched_barrier(0)
; template <class Epi, class Sched, bool ALIGN_EPI = false, bool SP2 = false>
; __device__ __forceinline__ void gemm_phase(PG8_LAS unsigned char* lds, const Gemm g, const Sched& S, const Epi& E) {
;     ...
;         for (int t = 0; t < nt; t += 2) {
;             const bool last = (t == nt - 2);
;             const char* a1 = cA + (size_t)(t + 1) * kstep;
;             const char* a2 = last ? nA : cA + (size_t)(t + 2) * kstep; const char* b2 = last ? nB : cB + (size_t)(t + 2) * kstep;
;     ...
;             PG8_LDA(At, 1, 1); PG8_STAGE(PG8_SB(1, 0), b3, voffB); PG8_STAGE(PG8_SB(1, 1), b3 + hstep, voffB); PG8_STAGE(PG8_SA(1, 0), a3, voffA);
;             PG8_WAIT_V(8); PG8_WAIT_L(0); PG8_BAR; PG8_MMA(1, 0, At, B0); PG8_MMA(1, 1, At, B1); PG8_BAR; PG8_SCHED;
	s_add_i32 s22, s33, s31
	v_lshl_add_u64 v[144:145], v[144:145], 0, s[8:9]
	s_mov_b32 m0, s22
	ds_read_b128 v[198:201], v151 offset:49152
	ds_read_b128 v[202:205], v151 offset:50176
	ds_read_b128 v[206:209], v151 offset:51200
	ds_read_b128 v[210:213], v151 offset:52224
	ds_read_b128 v[214:217], v151 offset:53248
	ds_read_b128 v[218:221], v151 offset:54272
	ds_read_b128 v[222:225], v151 offset:55296
	ds_read_b128 v[226:229], v151 offset:56320
	global_load_lds_dwordx4 v[144:145], off
	s_add_i32 m0, s22, 0x2000
	s_add_u32 s22, s26, 0xb0080
	v_lshl_add_u64 v[144:145], v[160:161], 0, s[8:9]
	s_addc_u32 s23, s27, 0
	s_add_i32 s26, s55, s31
	global_load_lds_dwordx4 v[144:145], off
	v_lshl_add_u64 v[144:145], s[22:23], 0, v[130:131]
	s_mov_b32 m0, s26
	s_nop 0
	global_load_lds_dwordx4 v[144:145], off
	v_lshl_add_u64 v[144:145], s[22:23], 0, v[134:135]
	s_add_i32 m0, s26, 0x2000
	s_nop 0
	global_load_lds_dwordx4 v[144:145], off
	v_lshl_add_u64 v[144:145], v[184:185], 0, s[8:9]
	s_mov_b32 m0, s39
	s_nop 0
	global_load_lds_dwordx4 v[144:145], off
	v_lshl_add_u64 v[144:145], v[230:231], 0, s[8:9]
	s_mov_b32 m0, s40
	s_nop 0
	global_load_lds_dwordx4 v[144:145], off
	s_waitcnt vmcnt(8)
	s_waitcnt lgkmcnt(0)
	s_barrier
	s_setprio 1
	s_waitcnt lgkmcnt(0)
	v_mfma_f32_16x16x32_bf16 v[60:63], v[152:155], v[198:201], v[60:63]
	v_mfma_f32_16x16x32_bf16 v[56:59], v[168:171], v[198:201], v[56:59]
	v_mfma_f32_16x16x32_bf16 v[52:55], v[152:155], v[206:209], v[52:55]
	v_mfma_f32_16x16x32_bf16 v[44:47], v[168:171], v[206:209], v[44:47]
	v_mfma_f32_16x16x32_bf16 v[36:39], v[152:155], v[214:217], v[36:39]
	v_mfma_f32_16x16x32_bf16 v[28:31], v[168:171], v[214:217], v[28:31]
	v_mfma_f32_16x16x32_bf16 v[20:23], v[152:155], v[222:225], v[20:23]
	v_mfma_f32_16x16x32_bf16 v[12:15], v[168:171], v[222:225], v[12:15]
	v_mfma_f32_16x16x32_bf16 v[60:63], v[156:159], v[202:205], v[60:63]
	v_mfma_f32_16x16x32_bf16 v[56:59], v[172:175], v[202:205], v[56:59]
	v_mfma_f32_16x16x32_bf16 v[52:55], v[156:159], v[210:213], v[52:55]
	v_mfma_f32_16x16x32_bf16 v[44:47], v[172:175], v[210:213], v[44:47]
	v_mfma_f32_16x16x32_bf16 v[36:39], v[156:159], v[218:221], v[36:39]
	v_mfma_f32_16x16x32_bf16 v[28:31], v[172:175], v[218:221], v[28:31]
	v_mfma_f32_16x16x32_bf16 v[20:23], v[156:159], v[226:229], v[20:23]
	v_mfma_f32_16x16x32_bf16 v[12:15], v[172:175], v[226:229], v[12:15]
	v_mfma_f32_16x16x32_bf16 v[48:51], v[176:179], v[198:201], v[48:51]
	v_mfma_f32_16x16x32_bf16 v[40:43], v[190:193], v[198:201], v[40:43]
	v_mfma_f32_16x16x32_bf16 v[32:35], v[176:179], v[206:209], v[32:35]
	v_mfma_f32_16x16x32_bf16 v[24:27], v[190:193], v[206:209], v[24:27]
	v_mfma_f32_16x16x32_bf16 v[16:19], v[176:179], v[214:217], v[16:19]
	v_mfma_f32_16x16x32_bf16 v[8:11], v[190:193], v[214:217], v[8:11]
	v_mfma_f32_16x16x32_bf16 v[4:7], v[176:179], v[222:225], v[4:7]
	v_mfma_f32_16x16x32_bf16 v[0:3], v[190:193], v[222:225], v[0:3]
	v_mfma_f32_16x16x32_bf16 v[48:51], v[180:183], v[202:205], v[48:51]
	v_mfma_f32_16x16x32_bf16 v[40:43], v[194:197], v[202:205], v[40:43]
	v_mfma_f32_16x16x32_bf16 v[32:35], v[180:183], v[210:213], v[32:35]
	v_mfma_f32_16x16x32_bf16 v[24:27], v[194:197], v[210:213], v[24:27]
	v_mfma_f32_16x16x32_bf16 v[16:19], v[180:183], v[218:221], v[16:19]
	v_mfma_f32_16x16x32_bf16 v[8:11], v[194:197], v[218:221], v[8:11]
	v_mfma_f32_16x16x32_bf16 v[4:7], v[180:183], v[226:229], v[4:7]
	v_mfma_f32_16x16x32_bf16 v[0:3], v[194:197], v[226:229], v[0:3]
	s_setprio 0
	s_barrier
	s_add_i32 s54, s54, 2
	s_add_u32 s52, s52, 0x100
	s_addc_u32 s53, s53, 0
	s_cmp_gt_u32 s54, 41
	s_mov_b64 s[22:23], s[24:25]
	s_cbranch_scc0 .LBB0_1663
	s_and_b64 vcc, exec, s[10:11]
	s_cbranch_vccz .LBB0_1666
	s_barrier
